# K-loop MFMA order variant 32_chain_b (+ load segments without VALU copies)
# baseline (speedup 1.0000x reference)
; #define PG8_STAGE(bufoff, gbase, voff) do { const char* gb_ = (const char*)(gbase); asm volatile("" : "+s"(gb_)); _Pragma("unroll") for (int _i = 0; _i < 2; ++_i) { unsigned vo_ = (voff)[_i]; asm volatile("" : "+v"(vo_));        \
;         __builtin_amdgcn_global_load_lds((const unsigned*)(gb_ + vo_), (PG8_LAS unsigned*)(lds + (bufoff) + ldsw + _i * 8192), 16, 0, 0); } } while (0)
; #define PG8_LDA(dst, b, h) do { _Pragma("unroll") for (int m = 0; m < 4; ++m) _Pragma("unroll") for (int k = 0; k < 2; ++k) dst[m][k] = *(const PG8_LAS bf16x8*)(lds + PG8_SA(b, h) + aoff + m * 2048 + k * 1024); } while (0)
; #define PG8_LDB(dst, b, h) do { _Pragma("unroll") for (int n = 0; n < 2; ++n) _Pragma("unroll") for (int k = 0; k < 2; ++k) dst[n][k] = *(const PG8_LAS bf16x8*)(lds + PG8_SB(b, h) + boff + n * 2048 + k * 1024); } while (0)
; #define PG8_MMA(ai, bj, At, Bt) do { __builtin_amdgcn_s_setprio(1); _Pragma("unroll") for (int m = 0; m < 4; ++m) _Pragma("unroll") for (int n = 0; n < 2; ++n) _Pragma("unroll") for (int k = 0; k < 2; ++k) \
;         acc[ai][bj][m][n] = __builtin_amdgcn_mfma_f32_16x16x32_bf16(Bt[n][k], At[m][k], acc[ai][bj][m][n], 0, 0, 0); __builtin_amdgcn_s_setprio(0); } while (0)
; #define PG8_WAIT_V(n) asm volatile("s_waitcnt vmcnt(" #n ")" ::: "memory")
; template <class Epi, class Sched, bool ALIGN_EPI = false, bool SP2 = false>
; __device__ __forceinline__ void gemm_phase(PG8_LAS unsigned char* lds, const Gemm g, const Sched& S, const Epi& E) {
;     ...
;             const bool last = (t == nt - 2);
;             const char* a1 = cA + (size_t)(t + 1) * kstep;
;             const char* a2 = last ? nA : cA + (size_t)(t + 2) * kstep; const char* b2 = last ? nB : cB + (size_t)(t + 2) * kstep;
;             const char* a3 = a2 + kstep; const char* b3 = b2 + kstep;
;             if (last && has_next) S.a_ready(nxt);
;             if constexpr (SP2) {
;             PG8_LDB(B0, 0, 0); PG8_LDB(B1, 0, 1); PG8_SCHED; PG8_LDA(At, 0, 0); PG8_STAGE(PG8_SA(1, 1), a1 + hstep, voffA);
;             PG8_WAIT_V(8); PG8_WAIT_L(0); PG8_BAR; PG8_MMA(0, 0, At, B0); PG8_MMA(0, 1, At, B1); PG8_BAR; PG8_SCHED;
;             PG8_LDA(At, 0, 1); PG8_STAGE(PG8_SB(0, 0), b2, voffB); PG8_STAGE(PG8_SB(0, 1), b2 + hstep, voffB); PG8_STAGE(PG8_SA(0, 0), a2, voffA);
;             PG8_WAIT_V(8); PG8_WAIT_L(0); PG8_BAR; PG8_MMA(1, 0, At, B0); PG8_MMA(1, 1, At, B1); PG8_BAR; PG8_SCHED;
.LBB0_232:
	s_add_u32 s2, s0, 0x100
	s_addc_u32 s3, s1, 0
	s_cmp_eq_u32 s30, 28
	s_cselect_b32 s10, s25, s2
	s_cselect_b32 s11, s24, s3
	s_cselect_b32 s8, s27, s28
	s_cselect_b32 s9, s26, s29
	s_add_u32 s6, s10, 0x80
	s_addc_u32 s7, s11, 0
	s_add_i32 s31, 0, 0x10000
	s_add_i32 s33, 0, 0x14000
	ds_read_b128 v[66:69], v244
	ds_read_b128 v[70:73], v244 offset:1024
	ds_read_b128 v[74:77], v244 offset:2048
	ds_read_b128 v[78:81], v244 offset:3072
	ds_read_b128 v[146:149], v244 offset:16384
	ds_read_b128 v[150:153], v244 offset:17408
	ds_read_b128 v[154:157], v244 offset:18432
	ds_read_b128 v[158:161], v244 offset:19456
	s_add_u32 s0, s0, 0x80080
	s_addc_u32 s1, s1, 0
	ds_read_b128 v[178:181], v223
	ds_read_b128 v[248:251], v223 offset:1024
	ds_read_b128 v[252:255], v223 offset:2048
	ds_read_b128 v[196:199], v223 offset:3072
	ds_read_b128 v[200:203], v223 offset:4096
	ds_read_b128 v[204:207], v223 offset:5120
	ds_read_b128 v[208:211], v223 offset:6144
	ds_read_b128 v[212:215], v223 offset:7168
	s_add_i32 m0, s13, 0xc000
	s_nop 0
	global_load_lds_dwordx4 v1, s[0:1]
	s_add_i32 m0, s13, 0xe000
	s_nop 0
	global_load_lds_dwordx4 v191, s[0:1]
	s_waitcnt vmcnt(8)
	s_waitcnt lgkmcnt(0)
	s_barrier
	s_setprio 1
	s_waitcnt lgkmcnt(0)
	v_mfma_f32_16x16x32_bf16 v[142:145], v[66:69], v[178:181], v[142:145]
	v_mfma_f32_16x16x32_bf16 v[142:145], v[70:73], v[248:251], v[142:145]
	v_mfma_f32_16x16x32_bf16 v[134:137], v[66:69], v[252:255], v[134:137]
	v_mfma_f32_16x16x32_bf16 v[134:137], v[70:73], v[196:199], v[134:137]
	v_mfma_f32_16x16x32_bf16 v[126:129], v[66:69], v[200:203], v[126:129]
	v_mfma_f32_16x16x32_bf16 v[126:129], v[70:73], v[204:207], v[126:129]
	v_mfma_f32_16x16x32_bf16 v[118:121], v[66:69], v[208:211], v[118:121]
	v_mfma_f32_16x16x32_bf16 v[118:121], v[70:73], v[212:215], v[118:121]
	v_mfma_f32_16x16x32_bf16 v[138:141], v[74:77], v[178:181], v[138:141]
	v_mfma_f32_16x16x32_bf16 v[138:141], v[78:81], v[248:251], v[138:141]
	v_mfma_f32_16x16x32_bf16 v[130:133], v[74:77], v[252:255], v[130:133]
	v_mfma_f32_16x16x32_bf16 v[130:133], v[78:81], v[196:199], v[130:133]
	v_mfma_f32_16x16x32_bf16 v[122:125], v[74:77], v[200:203], v[122:125]
	v_mfma_f32_16x16x32_bf16 v[122:125], v[78:81], v[204:207], v[122:125]
	v_mfma_f32_16x16x32_bf16 v[114:117], v[74:77], v[208:211], v[114:117]
	v_mfma_f32_16x16x32_bf16 v[114:117], v[78:81], v[212:215], v[114:117]
	s_setprio 0
	s_setprio 1
	v_mfma_f32_16x16x32_bf16 v[62:65], v[146:149], v[178:181], v[62:65]
	v_mfma_f32_16x16x32_bf16 v[62:65], v[150:153], v[248:251], v[62:65]
	v_mfma_f32_16x16x32_bf16 v[54:57], v[146:149], v[252:255], v[54:57]
	v_mfma_f32_16x16x32_bf16 v[54:57], v[150:153], v[196:199], v[54:57]
	v_mfma_f32_16x16x32_bf16 v[46:49], v[146:149], v[200:203], v[46:49]
	v_mfma_f32_16x16x32_bf16 v[46:49], v[150:153], v[204:207], v[46:49]
	v_mfma_f32_16x16x32_bf16 v[38:41], v[146:149], v[208:211], v[38:41]
	v_mfma_f32_16x16x32_bf16 v[38:41], v[150:153], v[212:215], v[38:41]
	v_mfma_f32_16x16x32_bf16 v[58:61], v[154:157], v[178:181], v[58:61]
	v_mfma_f32_16x16x32_bf16 v[58:61], v[158:161], v[248:251], v[58:61]
	v_mfma_f32_16x16x32_bf16 v[50:53], v[154:157], v[252:255], v[50:53]
	v_mfma_f32_16x16x32_bf16 v[50:53], v[158:161], v[196:199], v[50:53]
	v_mfma_f32_16x16x32_bf16 v[42:45], v[154:157], v[200:203], v[42:45]
	v_mfma_f32_16x16x32_bf16 v[42:45], v[158:161], v[204:207], v[42:45]
	v_mfma_f32_16x16x32_bf16 v[34:37], v[154:157], v[208:211], v[34:37]
	v_mfma_f32_16x16x32_bf16 v[34:37], v[158:161], v[212:215], v[34:37]
	s_setprio 0
	s_barrier
	s_mov_b64 s[0:1], s[8:9]
	s_add_i32 s31, s31, s12
	ds_read_b128 v[178:181], v223 offset:16384
	ds_read_b128 v[248:251], v223 offset:17408
	ds_read_b128 v[252:255], v223 offset:18432
	ds_read_b128 v[196:199], v223 offset:19456
	ds_read_b128 v[200:203], v223 offset:20480
	ds_read_b128 v[204:207], v223 offset:21504
	ds_read_b128 v[208:211], v223 offset:22528
	ds_read_b128 v[212:215], v223 offset:23552
	s_mov_b32 m0, s31
	s_nop 0
	global_load_lds_dwordx4 v189, s[0:1]
	s_add_i32 m0, s31, 0x2000
	s_nop 0
	global_load_lds_dwordx4 v219, s[0:1]
	s_add_u32 s0, s8, 0x80000
	s_addc_u32 s1, s9, 0
	s_add_i32 s31, s33, s12
	s_mov_b32 m0, s31
	s_nop 0
	global_load_lds_dwordx4 v189, s[0:1]
	s_add_i32 m0, s31, 0x2000
	s_nop 0
	global_load_lds_dwordx4 v219, s[0:1]
	s_mov_b64 s[0:1], s[10:11]
	s_mov_b32 m0, s13
	s_nop 0
	global_load_lds_dwordx4 v1, s[0:1]
	s_mov_b32 m0, s14
	s_nop 0
	global_load_lds_dwordx4 v191, s[0:1]
	s_waitcnt vmcnt(8)
	s_waitcnt lgkmcnt(0)
	s_barrier
	s_setprio 1
	s_waitcnt lgkmcnt(0)
	v_mfma_f32_16x16x32_bf16 v[110:113], v[66:69], v[178:181], v[110:113]
	v_mfma_f32_16x16x32_bf16 v[110:113], v[70:73], v[248:251], v[110:113]
	v_mfma_f32_16x16x32_bf16 v[102:105], v[66:69], v[252:255], v[102:105]
	v_mfma_f32_16x16x32_bf16 v[102:105], v[70:73], v[196:199], v[102:105]
	v_mfma_f32_16x16x32_bf16 v[94:97], v[66:69], v[200:203], v[94:97]
	v_mfma_f32_16x16x32_bf16 v[94:97], v[70:73], v[204:207], v[94:97]
	v_mfma_f32_16x16x32_bf16 v[66:69], v[66:69], v[208:211], v[86:89]
	v_mfma_f32_16x16x32_bf16 v[66:69], v[70:73], v[212:215], v[66:69]
	v_mfma_f32_16x16x32_bf16 v[106:109], v[74:77], v[178:181], v[106:109]
	v_mfma_f32_16x16x32_bf16 v[106:109], v[78:81], v[248:251], v[106:109]
	v_mfma_f32_16x16x32_bf16 v[98:101], v[74:77], v[252:255], v[98:101]
	v_mfma_f32_16x16x32_bf16 v[98:101], v[78:81], v[196:199], v[98:101]
	v_mfma_f32_16x16x32_bf16 v[90:93], v[74:77], v[200:203], v[90:93]
	v_mfma_f32_16x16x32_bf16 v[90:93], v[78:81], v[204:207], v[90:93]
	v_mfma_f32_16x16x32_bf16 v[70:73], v[74:77], v[208:211], v[82:85]
	v_mfma_f32_16x16x32_bf16 v[70:73], v[78:81], v[212:215], v[70:73]
	s_setprio 0
	s_setprio 1
	v_mfma_f32_16x16x32_bf16 v[30:33], v[146:149], v[178:181], v[30:33]
	v_mfma_f32_16x16x32_bf16 v[30:33], v[150:153], v[248:251], v[30:33]
	v_mfma_f32_16x16x32_bf16 v[22:25], v[146:149], v[252:255], v[22:25]
	v_mfma_f32_16x16x32_bf16 v[22:25], v[150:153], v[196:199], v[22:25]
	v_mfma_f32_16x16x32_bf16 v[14:17], v[146:149], v[200:203], v[14:17]
	v_mfma_f32_16x16x32_bf16 v[14:17], v[150:153], v[204:207], v[14:17]
	v_mfma_f32_16x16x32_bf16 v[6:9], v[146:149], v[208:211], v[6:9]
	v_mfma_f32_16x16x32_bf16 v[6:9], v[150:153], v[212:215], v[6:9]
	v_mfma_f32_16x16x32_bf16 v[26:29], v[154:157], v[178:181], v[26:29]
	v_mfma_f32_16x16x32_bf16 v[26:29], v[158:161], v[248:251], v[26:29]
	v_mfma_f32_16x16x32_bf16 v[18:21], v[154:157], v[252:255], v[18:21]
	v_mfma_f32_16x16x32_bf16 v[18:21], v[158:161], v[196:199], v[18:21]
	v_mfma_f32_16x16x32_bf16 v[10:13], v[154:157], v[200:203], v[10:13]
	v_mfma_f32_16x16x32_bf16 v[10:13], v[158:161], v[204:207], v[10:13]
	v_mfma_f32_16x16x32_bf16 v[2:5], v[154:157], v[208:211], v[2:5]
	v_mfma_f32_16x16x32_bf16 v[2:5], v[158:161], v[212:215], v[2:5]
	s_setprio 0
	s_barrier
; #define PG8_LDA(dst, b, h) do { _Pragma("unroll") for (int m = 0; m < 4; ++m) _Pragma("unroll") for (int k = 0; k < 2; ++k) dst[m][k] = *(const PG8_LAS bf16x8*)(lds + PG8_SA(b, h) + aoff + m * 2048 + k * 1024); } while (0)
; #define PG8_WAIT_V(n) asm volatile("s_waitcnt vmcnt(" #n ")" ::: "memory")
; template <class Epi, class Sched, bool ALIGN_EPI = false, bool SP2 = false>
; __device__ __forceinline__ void gemm_phase(PG8_LAS unsigned char* lds, const Gemm g, const Sched& S, const Epi& E) {
;     ...
;             PG8_LDB(B0, 1, 0); PG8_LDB(B1, 1, 1); PG8_SCHED; PG8_LDA(At, 1, 0); PG8_STAGE(PG8_SA(0, 1), a2 + hstep, voffA);
;             PG8_WAIT_V(8); PG8_WAIT_L(0); PG8_BAR; PG8_MMA(0, 0, At, B0); PG8_MMA(0, 1, At, B1); PG8_BAR; PG8_SCHED;
;             PG8_LDA(At, 1, 1); PG8_STAGE(PG8_SB(1, 0), b3, voffB); PG8_STAGE(PG8_SB(1, 1), b3 + hstep, voffB); PG8_STAGE(PG8_SA(1, 0), a3, voffA);
;             PG8_WAIT_V(8); PG8_WAIT_L(0); PG8_BAR; PG8_MMA(1, 0, At, B0); PG8_MMA(1, 1, At, B1); PG8_BAR; PG8_SCHED;
;             } else {
;             PG8_LDB(B0, 0, 0); PG8_SCHED; PG8_LDA(At, 0, 0); PG8_STAGE(PG8_SA(1, 1), a1 + hstep, voffA);
;             PG8_WAIT_L(8); PG8_BAR; PG8_WAIT_L(0); PG8_MMA(0, 0, At, B0); PG8_BAR; PG8_SCHED;
;             PG8_LDB(B1, 0, 1); PG8_STAGE(PG8_SB(0, 0), b2, voffB);
;             PG8_BAR; PG8_WAIT_L(0); PG8_MMA(0, 1, At, B1); PG8_BAR;
;             PG8_LDA(At, 0, 1); PG8_STAGE(PG8_SA(0, 0), a2, voffA);
;             PG8_BAR; PG8_WAIT_L(0); PG8_MMA(1, 0, At, B0); PG8_BAR; PG8_SCHED;
;             PG8_STAGE(PG8_SB(0, 1), b2 + hstep, voffB);
;             PG8_WAIT_V(6); PG8_BAR; PG8_MMA(1, 1, At, B1); PG8_BAR;
;             PG8_LDB(B0, 1, 0); PG8_SCHED; PG8_LDA(At, 1, 0); PG8_STAGE(PG8_SA(0, 1), a2 + hstep, voffA);
;             PG8_WAIT_L(8); PG8_BAR; PG8_WAIT_L(0); PG8_MMA(0, 0, At, B0); PG8_BAR; PG8_SCHED;
;             PG8_LDB(B1, 1, 1); PG8_STAGE(PG8_SB(1, 0), b3, voffB);
;             PG8_BAR; PG8_WAIT_L(0); PG8_MMA(0, 1, At, B1); PG8_BAR;
;             PG8_LDA(At, 1, 1); PG8_STAGE(PG8_SA(1, 0), a3, voffA);
;             PG8_BAR; PG8_WAIT_L(0); PG8_MMA(1, 0, At, B0); PG8_BAR; PG8_SCHED;
;             PG8_STAGE(PG8_SB(1, 1), b3 + hstep, voffB);
;             PG8_WAIT_V(6); PG8_BAR; PG8_MMA(1, 1, At, B1); PG8_BAR;
;             }
;         }
;         if constexpr (ALIGN_EPI) { if (wr == 0) PG8_BAR; }
	s_add_i32 s31, 0, 0x18000
	s_add_i32 s33, 0, 0x1c000
	ds_read_b128 v[74:77], v244 offset:32768
	ds_read_b128 v[78:81], v244 offset:33792
	ds_read_b128 v[82:85], v244 offset:34816
	ds_read_b128 v[146:149], v244 offset:35840
	ds_read_b128 v[150:153], v244 offset:49152
	ds_read_b128 v[154:157], v244 offset:50176
	ds_read_b128 v[158:161], v244 offset:51200
	ds_read_b128 v[178:181], v244 offset:52224
	s_add_u32 s0, s10, 0x80000
	s_addc_u32 s1, s11, 0
	s_mov_b32 m0, s15
	ds_read_b128 v[86:89], v223 offset:32768
	ds_read_b128 v[248:251], v223 offset:33792
	ds_read_b128 v[252:255], v223 offset:34816
	ds_read_b128 v[196:199], v223 offset:35840
	ds_read_b128 v[200:203], v223 offset:36864
	ds_read_b128 v[204:207], v223 offset:37888
	ds_read_b128 v[208:211], v223 offset:38912
	ds_read_b128 v[212:215], v223 offset:39936
	s_nop 0
	global_load_lds_dwordx4 v1, s[0:1]
	s_mov_b32 m0, s16
	s_nop 0
	global_load_lds_dwordx4 v191, s[0:1]
	s_waitcnt vmcnt(8)
	s_waitcnt lgkmcnt(0)
	s_barrier
	s_setprio 1
	s_waitcnt lgkmcnt(0)
	v_mfma_f32_16x16x32_bf16 v[142:145], v[74:77], v[86:89], v[142:145]
	v_mfma_f32_16x16x32_bf16 v[142:145], v[78:81], v[248:251], v[142:145]
	v_mfma_f32_16x16x32_bf16 v[134:137], v[74:77], v[252:255], v[134:137]
	v_mfma_f32_16x16x32_bf16 v[134:137], v[78:81], v[196:199], v[134:137]
	v_mfma_f32_16x16x32_bf16 v[126:129], v[74:77], v[200:203], v[126:129]
	v_mfma_f32_16x16x32_bf16 v[126:129], v[78:81], v[204:207], v[126:129]
	v_mfma_f32_16x16x32_bf16 v[118:121], v[74:77], v[208:211], v[118:121]
	v_mfma_f32_16x16x32_bf16 v[118:121], v[78:81], v[212:215], v[118:121]
	v_mfma_f32_16x16x32_bf16 v[138:141], v[82:85], v[86:89], v[138:141]
	v_mfma_f32_16x16x32_bf16 v[138:141], v[146:149], v[248:251], v[138:141]
	v_mfma_f32_16x16x32_bf16 v[130:133], v[82:85], v[252:255], v[130:133]
	v_mfma_f32_16x16x32_bf16 v[130:133], v[146:149], v[196:199], v[130:133]
	v_mfma_f32_16x16x32_bf16 v[122:125], v[82:85], v[200:203], v[122:125]
	v_mfma_f32_16x16x32_bf16 v[122:125], v[146:149], v[204:207], v[122:125]
	v_mfma_f32_16x16x32_bf16 v[114:117], v[82:85], v[208:211], v[114:117]
	v_mfma_f32_16x16x32_bf16 v[114:117], v[146:149], v[212:215], v[114:117]
	s_setprio 0
	s_setprio 1
	v_mfma_f32_16x16x32_bf16 v[62:65], v[150:153], v[86:89], v[62:65]
	v_mfma_f32_16x16x32_bf16 v[62:65], v[154:157], v[248:251], v[62:65]
	v_mfma_f32_16x16x32_bf16 v[54:57], v[150:153], v[252:255], v[54:57]
	v_mfma_f32_16x16x32_bf16 v[54:57], v[154:157], v[196:199], v[54:57]
	v_mfma_f32_16x16x32_bf16 v[46:49], v[150:153], v[200:203], v[46:49]
	v_mfma_f32_16x16x32_bf16 v[46:49], v[154:157], v[204:207], v[46:49]
	v_mfma_f32_16x16x32_bf16 v[38:41], v[150:153], v[208:211], v[38:41]
	v_mfma_f32_16x16x32_bf16 v[38:41], v[154:157], v[212:215], v[38:41]
	v_mfma_f32_16x16x32_bf16 v[58:61], v[158:161], v[86:89], v[58:61]
	v_mfma_f32_16x16x32_bf16 v[58:61], v[178:181], v[248:251], v[58:61]
	v_mfma_f32_16x16x32_bf16 v[50:53], v[158:161], v[252:255], v[50:53]
	v_mfma_f32_16x16x32_bf16 v[50:53], v[178:181], v[196:199], v[50:53]
	v_mfma_f32_16x16x32_bf16 v[42:45], v[158:161], v[200:203], v[42:45]
	v_mfma_f32_16x16x32_bf16 v[42:45], v[178:181], v[204:207], v[42:45]
	v_mfma_f32_16x16x32_bf16 v[34:37], v[158:161], v[208:211], v[34:37]
	v_mfma_f32_16x16x32_bf16 v[34:37], v[178:181], v[212:215], v[34:37]
	s_setprio 0
	s_barrier
	s_add_u32 s0, s8, 0x80
	s_addc_u32 s1, s9, 0
	s_add_i32 s10, s31, s12
	ds_read_b128 v[248:251], v223 offset:49152
	ds_read_b128 v[252:255], v223 offset:50176
	ds_read_b128 v[196:199], v223 offset:51200
	ds_read_b128 v[200:203], v223 offset:52224
	ds_read_b128 v[204:207], v223 offset:53248
	ds_read_b128 v[208:211], v223 offset:54272
	ds_read_b128 v[212:215], v223 offset:55296
	ds_read_b128 v[224:227], v223 offset:56320
	s_mov_b32 m0, s10
	s_nop 0
	global_load_lds_dwordx4 v189, s[0:1]
	s_add_i32 m0, s10, 0x2000
	s_nop 0
	global_load_lds_dwordx4 v219, s[0:1]
	s_add_u32 s0, s8, 0x80080
	s_addc_u32 s1, s9, 0
	s_add_i32 s8, s33, s12
	s_mov_b32 m0, s8
	s_nop 0
	global_load_lds_dwordx4 v189, s[0:1]
	s_add_i32 m0, s8, 0x2000
	s_nop 0
	global_load_lds_dwordx4 v219, s[0:1]
	s_mov_b32 m0, s19
	s_nop 0
	global_load_lds_dwordx4 v1, s[6:7]
	s_mov_b32 m0, s20
	s_nop 0
	global_load_lds_dwordx4 v191, s[6:7]
	s_waitcnt vmcnt(8)
	s_waitcnt lgkmcnt(0)
	s_barrier
	s_setprio 1
	s_waitcnt lgkmcnt(0)
	v_mfma_f32_16x16x32_bf16 v[86:89], v[74:77], v[248:251], v[110:113]
	v_mfma_f32_16x16x32_bf16 v[110:113], v[78:81], v[252:255], v[86:89]
	v_mfma_f32_16x16x32_bf16 v[66:69], v[74:77], v[212:215], v[66:69]
	v_mfma_f32_16x16x32_bf16 v[86:89], v[82:85], v[248:251], v[106:109]
	v_mfma_f32_16x16x32_bf16 v[106:109], v[146:149], v[252:255], v[86:89]
	v_mfma_f32_16x16x32_bf16 v[86:89], v[74:77], v[196:199], v[102:105]
	v_mfma_f32_16x16x32_bf16 v[102:105], v[78:81], v[200:203], v[86:89]
	v_mfma_f32_16x16x32_bf16 v[86:89], v[82:85], v[196:199], v[98:101]
	v_mfma_f32_16x16x32_bf16 v[98:101], v[146:149], v[200:203], v[86:89]
	v_mfma_f32_16x16x32_bf16 v[86:89], v[74:77], v[204:207], v[94:97]
	v_mfma_f32_16x16x32_bf16 v[94:97], v[78:81], v[208:211], v[86:89]
	v_mfma_f32_16x16x32_bf16 v[86:89], v[82:85], v[204:207], v[90:93]
	v_mfma_f32_16x16x32_bf16 v[90:93], v[146:149], v[208:211], v[86:89]
	v_mfma_f32_16x16x32_bf16 v[86:89], v[78:81], v[224:227], v[66:69]
	v_mfma_f32_16x16x32_bf16 v[66:69], v[82:85], v[212:215], v[70:73]
	v_mfma_f32_16x16x32_bf16 v[82:85], v[146:149], v[224:227], v[66:69]
	s_setprio 0
	s_setprio 1
	v_mfma_f32_16x16x32_bf16 v[30:33], v[150:153], v[248:251], v[30:33]
	v_mfma_f32_16x16x32_bf16 v[30:33], v[154:157], v[252:255], v[30:33]
	v_mfma_f32_16x16x32_bf16 v[22:25], v[150:153], v[196:199], v[22:25]
	v_mfma_f32_16x16x32_bf16 v[22:25], v[154:157], v[200:203], v[22:25]
	v_mfma_f32_16x16x32_bf16 v[14:17], v[150:153], v[204:207], v[14:17]
	v_mfma_f32_16x16x32_bf16 v[14:17], v[154:157], v[208:211], v[14:17]
	v_mfma_f32_16x16x32_bf16 v[6:9], v[150:153], v[212:215], v[6:9]
	v_mfma_f32_16x16x32_bf16 v[6:9], v[154:157], v[224:227], v[6:9]
	v_mfma_f32_16x16x32_bf16 v[26:29], v[158:161], v[248:251], v[26:29]
	v_mfma_f32_16x16x32_bf16 v[26:29], v[178:181], v[252:255], v[26:29]
	v_mfma_f32_16x16x32_bf16 v[18:21], v[158:161], v[196:199], v[18:21]
	v_mfma_f32_16x16x32_bf16 v[18:21], v[178:181], v[200:203], v[18:21]
	v_mfma_f32_16x16x32_bf16 v[10:13], v[158:161], v[204:207], v[10:13]
	v_mfma_f32_16x16x32_bf16 v[10:13], v[178:181], v[208:211], v[10:13]
	v_mfma_f32_16x16x32_bf16 v[2:5], v[158:161], v[212:215], v[2:5]
	v_mfma_f32_16x16x32_bf16 v[2:5], v[178:181], v[224:227], v[2:5]
	s_setprio 0
	s_barrier
	s_add_i32 s30, s30, 2
	s_add_u32 s28, s28, 0x100
	s_addc_u32 s29, s29, 0
	s_cmp_gt_u32 s30, 29
	s_mov_b64 s[0:1], s[2:3]
	s_cbranch_scc0 .LBB0_232
	s_and_b64 vcc, exec, s[44:45]
	s_cbranch_vccz .LBB0_235
	s_barrier

; #define PG8_STAGE(bufoff, gbase, voff) do { const char* gb_ = (const char*)(gbase); asm volatile("" : "+s"(gb_)); _Pragma("unroll") for (int _i = 0; _i < 2; ++_i) { unsigned vo_ = (voff)[_i]; asm volatile("" : "+v"(vo_));        \
;         __builtin_amdgcn_global_load_lds((const unsigned*)(gb_ + vo_), (PG8_LAS unsigned*)(lds + (bufoff) + ldsw + _i * 8192), 16, 0, 0); } } while (0)
; #define PG8_LDA(dst, b, h) do { _Pragma("unroll") for (int m = 0; m < 4; ++m) _Pragma("unroll") for (int k = 0; k < 2; ++k) dst[m][k] = *(const PG8_LAS bf16x8*)(lds + PG8_SA(b, h) + aoff + m * 2048 + k * 1024); } while (0)
; #define PG8_LDB(dst, b, h) do { _Pragma("unroll") for (int n = 0; n < 2; ++n) _Pragma("unroll") for (int k = 0; k < 2; ++k) dst[n][k] = *(const PG8_LAS bf16x8*)(lds + PG8_SB(b, h) + boff + n * 2048 + k * 1024); } while (0)
; #define PG8_MMA(ai, bj, At, Bt) do { __builtin_amdgcn_s_setprio(1); _Pragma("unroll") for (int m = 0; m < 4; ++m) _Pragma("unroll") for (int n = 0; n < 2; ++n) _Pragma("unroll") for (int k = 0; k < 2; ++k) \
;         acc[ai][bj][m][n] = __builtin_amdgcn_mfma_f32_16x16x32_bf16(Bt[n][k], At[m][k], acc[ai][bj][m][n], 0, 0, 0); __builtin_amdgcn_s_setprio(0); } while (0)
; #define PG8_WAIT_V(n) asm volatile("s_waitcnt vmcnt(" #n ")" ::: "memory")
; template <class Epi, class Sched, bool ALIGN_EPI = false, bool SP2 = false>
; __device__ __forceinline__ void gemm_phase(PG8_LAS unsigned char* lds, const Gemm g, const Sched& S, const Epi& E) {
;     ...
;             const bool last = (t == nt - 2);
;             const char* a1 = cA + (size_t)(t + 1) * kstep;
;             const char* a2 = last ? nA : cA + (size_t)(t + 2) * kstep; const char* b2 = last ? nB : cB + (size_t)(t + 2) * kstep;
;             const char* a3 = a2 + kstep; const char* b3 = b2 + kstep;
;             if (last && has_next) S.a_ready(nxt);
;             if constexpr (SP2) {
;             PG8_LDB(B0, 0, 0); PG8_LDB(B1, 0, 1); PG8_SCHED; PG8_LDA(At, 0, 0); PG8_STAGE(PG8_SA(1, 1), a1 + hstep, voffA);
;             PG8_WAIT_V(8); PG8_WAIT_L(0); PG8_BAR; PG8_MMA(0, 0, At, B0); PG8_MMA(0, 1, At, B1); PG8_BAR; PG8_SCHED;
;             PG8_LDA(At, 0, 1); PG8_STAGE(PG8_SB(0, 0), b2, voffB); PG8_STAGE(PG8_SB(0, 1), b2 + hstep, voffB); PG8_STAGE(PG8_SA(0, 0), a2, voffA);
;             PG8_WAIT_V(8); PG8_WAIT_L(0); PG8_BAR; PG8_MMA(1, 0, At, B0); PG8_MMA(1, 1, At, B1); PG8_BAR; PG8_SCHED;
.LBB0_555:
	s_add_u32 s6, s4, 0x100
	s_addc_u32 s7, s5, 0
	s_cmp_eq_u32 s51, 28
	s_cselect_b32 s12, s35, s6
	s_cselect_b32 s13, s34, s7
	s_cselect_b32 s10, s39, s40
	s_cselect_b32 s11, s38, s49
	s_add_u32 s8, s12, 0x80
	s_addc_u32 s9, s13, 0
	s_add_i32 s56, 0, 0x10000
	s_add_i32 s57, 0, 0x14000
	ds_read_b128 v[26:29], v244
	ds_read_b128 v[30:33], v244 offset:1024
	ds_read_b128 v[98:101], v244 offset:2048
	ds_read_b128 v[102:105], v244 offset:3072
	ds_read_b128 v[146:149], v244 offset:16384
	ds_read_b128 v[150:153], v244 offset:17408
	ds_read_b128 v[154:157], v244 offset:18432
	ds_read_b128 v[158:161], v244 offset:19456
	s_add_u32 s4, s4, 0x80080
	s_addc_u32 s5, s5, 0
	ds_read_b128 v[248:251], v210
	ds_read_b128 v[252:255], v210 offset:1024
	ds_read_b128 v[186:189], v210 offset:2048
	ds_read_b128 v[190:193], v210 offset:3072
	ds_read_b128 v[194:197], v210 offset:4096
	ds_read_b128 v[198:201], v210 offset:5120
	ds_read_b128 v[202:205], v210 offset:6144
	ds_read_b128 v[212:215], v210 offset:7168
	s_add_i32 m0, s18, 0xc000
	s_nop 0
	global_load_lds_dwordx4 v1, s[4:5]
	s_add_i32 m0, s18, 0xe000
	s_nop 0
	global_load_lds_dwordx4 v164, s[4:5]
	s_waitcnt vmcnt(8)
	s_waitcnt lgkmcnt(0)
	s_barrier
	s_setprio 1
	s_waitcnt lgkmcnt(0)
	v_mfma_f32_16x16x32_bf16 v[142:145], v[26:29], v[248:251], v[142:145]
	v_mfma_f32_16x16x32_bf16 v[142:145], v[30:33], v[252:255], v[142:145]
	v_mfma_f32_16x16x32_bf16 v[134:137], v[26:29], v[186:189], v[134:137]
	v_mfma_f32_16x16x32_bf16 v[134:137], v[30:33], v[190:193], v[134:137]
	v_mfma_f32_16x16x32_bf16 v[126:129], v[26:29], v[194:197], v[126:129]
	v_mfma_f32_16x16x32_bf16 v[126:129], v[30:33], v[198:201], v[126:129]
	v_mfma_f32_16x16x32_bf16 v[118:121], v[26:29], v[202:205], v[118:121]
	v_mfma_f32_16x16x32_bf16 v[118:121], v[30:33], v[212:215], v[118:121]
	v_mfma_f32_16x16x32_bf16 v[138:141], v[98:101], v[248:251], v[138:141]
	v_mfma_f32_16x16x32_bf16 v[138:141], v[102:105], v[252:255], v[138:141]
	v_mfma_f32_16x16x32_bf16 v[130:133], v[98:101], v[186:189], v[130:133]
	v_mfma_f32_16x16x32_bf16 v[130:133], v[102:105], v[190:193], v[130:133]
	v_mfma_f32_16x16x32_bf16 v[122:125], v[98:101], v[194:197], v[122:125]
	v_mfma_f32_16x16x32_bf16 v[122:125], v[102:105], v[198:201], v[122:125]
	v_mfma_f32_16x16x32_bf16 v[114:117], v[98:101], v[202:205], v[114:117]
	v_mfma_f32_16x16x32_bf16 v[114:117], v[102:105], v[212:215], v[114:117]
	s_setprio 0
	s_setprio 1
	v_mfma_f32_16x16x32_bf16 v[70:73], v[146:149], v[248:251], v[70:73]
	v_mfma_f32_16x16x32_bf16 v[70:73], v[150:153], v[252:255], v[70:73]
	v_mfma_f32_16x16x32_bf16 v[62:65], v[146:149], v[186:189], v[62:65]
	v_mfma_f32_16x16x32_bf16 v[62:65], v[150:153], v[190:193], v[62:65]
	v_mfma_f32_16x16x32_bf16 v[54:57], v[146:149], v[194:197], v[54:57]
	v_mfma_f32_16x16x32_bf16 v[54:57], v[150:153], v[198:201], v[54:57]
	v_mfma_f32_16x16x32_bf16 v[46:49], v[146:149], v[202:205], v[46:49]
	v_mfma_f32_16x16x32_bf16 v[46:49], v[150:153], v[212:215], v[46:49]
	v_mfma_f32_16x16x32_bf16 v[66:69], v[154:157], v[248:251], v[66:69]
	v_mfma_f32_16x16x32_bf16 v[66:69], v[158:161], v[252:255], v[66:69]
	v_mfma_f32_16x16x32_bf16 v[58:61], v[154:157], v[186:189], v[58:61]
	v_mfma_f32_16x16x32_bf16 v[58:61], v[158:161], v[190:193], v[58:61]
	v_mfma_f32_16x16x32_bf16 v[50:53], v[154:157], v[194:197], v[50:53]
	v_mfma_f32_16x16x32_bf16 v[50:53], v[158:161], v[198:201], v[50:53]
	v_mfma_f32_16x16x32_bf16 v[42:45], v[154:157], v[202:205], v[42:45]
	v_mfma_f32_16x16x32_bf16 v[42:45], v[158:161], v[212:215], v[42:45]
	s_setprio 0
	s_barrier
	s_mov_b64 s[4:5], s[10:11]
	s_add_i32 s56, s56, s17
	ds_read_b128 v[248:251], v210 offset:16384
	ds_read_b128 v[252:255], v210 offset:17408
	ds_read_b128 v[186:189], v210 offset:18432
	ds_read_b128 v[190:193], v210 offset:19456
	ds_read_b128 v[194:197], v210 offset:20480
	ds_read_b128 v[198:201], v210 offset:21504
	ds_read_b128 v[202:205], v210 offset:22528
	ds_read_b128 v[212:215], v210 offset:23552
	s_mov_b32 m0, s56
	s_nop 0
	global_load_lds_dwordx4 v162, s[4:5]
	s_add_i32 m0, s56, 0x2000
	s_nop 0
	global_load_lds_dwordx4 v206, s[4:5]
	s_add_u32 s4, s10, 0x80000
	s_addc_u32 s5, s11, 0
	s_add_i32 s56, s57, s17
	s_mov_b32 m0, s56
	s_nop 0
	global_load_lds_dwordx4 v162, s[4:5]
	s_add_i32 m0, s56, 0x2000
	s_nop 0
	global_load_lds_dwordx4 v206, s[4:5]
	s_mov_b64 s[4:5], s[12:13]
	s_mov_b32 m0, s18
	s_nop 0
	global_load_lds_dwordx4 v1, s[4:5]
	s_mov_b32 m0, s19
	s_nop 0
	global_load_lds_dwordx4 v164, s[4:5]
	s_waitcnt vmcnt(8)
	s_waitcnt lgkmcnt(0)
	s_barrier
; #define PG8_STAGE(bufoff, gbase, voff) do { const char* gb_ = (const char*)(gbase); asm volatile("" : "+s"(gb_)); _Pragma("unroll") for (int _i = 0; _i < 2; ++_i) { unsigned vo_ = (voff)[_i]; asm volatile("" : "+v"(vo_));        \
;         __builtin_amdgcn_global_load_lds((const unsigned*)(gb_ + vo_), (PG8_LAS unsigned*)(lds + (bufoff) + ldsw + _i * 8192), 16, 0, 0); } } while (0)
; #define PG8_LDA(dst, b, h) do { _Pragma("unroll") for (int m = 0; m < 4; ++m) _Pragma("unroll") for (int k = 0; k < 2; ++k) dst[m][k] = *(const PG8_LAS bf16x8*)(lds + PG8_SA(b, h) + aoff + m * 2048 + k * 1024); } while (0)
; #define PG8_LDB(dst, b, h) do { _Pragma("unroll") for (int n = 0; n < 2; ++n) _Pragma("unroll") for (int k = 0; k < 2; ++k) dst[n][k] = *(const PG8_LAS bf16x8*)(lds + PG8_SB(b, h) + boff + n * 2048 + k * 1024); } while (0)
; #define PG8_MMA(ai, bj, At, Bt) do { __builtin_amdgcn_s_setprio(1); _Pragma("unroll") for (int m = 0; m < 4; ++m) _Pragma("unroll") for (int n = 0; n < 2; ++n) _Pragma("unroll") for (int k = 0; k < 2; ++k) \
;         acc[ai][bj][m][n] = __builtin_amdgcn_mfma_f32_16x16x32_bf16(Bt[n][k], At[m][k], acc[ai][bj][m][n], 0, 0, 0); __builtin_amdgcn_s_setprio(0); } while (0)
; #define PG8_WAIT_V(n) asm volatile("s_waitcnt vmcnt(" #n ")" ::: "memory")
; #define PG8_WAIT_L(n) asm volatile("s_waitcnt lgkmcnt(" #n ")" ::: "memory")
; #define PG8_BAR __builtin_amdgcn_s_barrier()
; #define PG8_SCHED __builtin_amdgcn_sched_barrier(0)
; template <class Epi, class Sched, bool ALIGN_EPI = false, bool SP2 = false>
; __device__ __forceinline__ void gemm_phase(PG8_LAS unsigned char* lds, const Gemm g, const Sched& S, const Epi& E) {
;     ...
;             PG8_WAIT_V(8); PG8_WAIT_L(0); PG8_BAR; PG8_MMA(0, 0, At, B0); PG8_MMA(0, 1, At, B1); PG8_BAR; PG8_SCHED;
;             PG8_LDA(At, 0, 1); PG8_STAGE(PG8_SB(0, 0), b2, voffB); PG8_STAGE(PG8_SB(0, 1), b2 + hstep, voffB); PG8_STAGE(PG8_SA(0, 0), a2, voffA);
;             PG8_WAIT_V(8); PG8_WAIT_L(0); PG8_BAR; PG8_MMA(1, 0, At, B0); PG8_MMA(1, 1, At, B1); PG8_BAR; PG8_SCHED;
;             PG8_LDB(B0, 1, 0); PG8_LDB(B1, 1, 1); PG8_SCHED; PG8_LDA(At, 1, 0); PG8_STAGE(PG8_SA(0, 1), a2 + hstep, voffA);
;             PG8_WAIT_V(8); PG8_WAIT_L(0); PG8_BAR; PG8_MMA(0, 0, At, B0); PG8_MMA(0, 1, At, B1); PG8_BAR; PG8_SCHED;
	s_setprio 1
	s_waitcnt lgkmcnt(0)
	v_mfma_f32_16x16x32_bf16 v[110:113], v[26:29], v[248:251], v[110:113]
	v_mfma_f32_16x16x32_bf16 v[110:113], v[30:33], v[252:255], v[110:113]
	v_mfma_f32_16x16x32_bf16 v[94:97], v[26:29], v[186:189], v[94:97]
	v_mfma_f32_16x16x32_bf16 v[94:97], v[30:33], v[190:193], v[94:97]
	v_mfma_f32_16x16x32_bf16 v[86:89], v[26:29], v[194:197], v[86:89]
	v_mfma_f32_16x16x32_bf16 v[86:89], v[30:33], v[198:201], v[86:89]
	v_mfma_f32_16x16x32_bf16 v[26:29], v[26:29], v[202:205], v[78:81]
	v_mfma_f32_16x16x32_bf16 v[26:29], v[30:33], v[212:215], v[26:29]
	v_mfma_f32_16x16x32_bf16 v[106:109], v[98:101], v[248:251], v[106:109]
	v_mfma_f32_16x16x32_bf16 v[106:109], v[102:105], v[252:255], v[106:109]
	v_mfma_f32_16x16x32_bf16 v[90:93], v[98:101], v[186:189], v[90:93]
	v_mfma_f32_16x16x32_bf16 v[90:93], v[102:105], v[190:193], v[90:93]
	v_mfma_f32_16x16x32_bf16 v[82:85], v[98:101], v[194:197], v[82:85]
	v_mfma_f32_16x16x32_bf16 v[82:85], v[102:105], v[198:201], v[82:85]
	v_mfma_f32_16x16x32_bf16 v[30:33], v[98:101], v[202:205], v[74:77]
	v_mfma_f32_16x16x32_bf16 v[30:33], v[102:105], v[212:215], v[30:33]
	s_setprio 0
	s_setprio 1
	v_mfma_f32_16x16x32_bf16 v[38:41], v[146:149], v[248:251], v[38:41]
	v_mfma_f32_16x16x32_bf16 v[38:41], v[150:153], v[252:255], v[38:41]
	v_mfma_f32_16x16x32_bf16 v[22:25], v[146:149], v[186:189], v[22:25]
	v_mfma_f32_16x16x32_bf16 v[22:25], v[150:153], v[190:193], v[22:25]
	v_mfma_f32_16x16x32_bf16 v[14:17], v[146:149], v[194:197], v[14:17]
	v_mfma_f32_16x16x32_bf16 v[14:17], v[150:153], v[198:201], v[14:17]
	v_mfma_f32_16x16x32_bf16 v[6:9], v[146:149], v[202:205], v[6:9]
	v_mfma_f32_16x16x32_bf16 v[6:9], v[150:153], v[212:215], v[6:9]
	v_mfma_f32_16x16x32_bf16 v[34:37], v[154:157], v[248:251], v[34:37]
	v_mfma_f32_16x16x32_bf16 v[34:37], v[158:161], v[252:255], v[34:37]
	v_mfma_f32_16x16x32_bf16 v[18:21], v[154:157], v[186:189], v[18:21]
	v_mfma_f32_16x16x32_bf16 v[18:21], v[158:161], v[190:193], v[18:21]
	v_mfma_f32_16x16x32_bf16 v[10:13], v[154:157], v[194:197], v[10:13]
	v_mfma_f32_16x16x32_bf16 v[10:13], v[158:161], v[198:201], v[10:13]
	v_mfma_f32_16x16x32_bf16 v[2:5], v[154:157], v[202:205], v[2:5]
	v_mfma_f32_16x16x32_bf16 v[2:5], v[158:161], v[212:215], v[2:5]
	s_setprio 0
	s_barrier
	s_add_i32 s56, 0, 0x18000
	s_add_i32 s57, 0, 0x1c000
	ds_read_b128 v[74:77], v244 offset:32768
	ds_read_b128 v[78:81], v244 offset:33792
	ds_read_b128 v[98:101], v244 offset:34816
	ds_read_b128 v[102:105], v244 offset:35840
	ds_read_b128 v[146:149], v244 offset:49152
	ds_read_b128 v[150:153], v244 offset:50176
	ds_read_b128 v[154:157], v244 offset:51200
	ds_read_b128 v[158:161], v244 offset:52224
	s_add_u32 s4, s12, 0x80000
	s_addc_u32 s5, s13, 0
	s_mov_b32 m0, s20
	ds_read_b128 v[248:251], v210 offset:32768
	ds_read_b128 v[252:255], v210 offset:33792
	ds_read_b128 v[186:189], v210 offset:34816
	ds_read_b128 v[190:193], v210 offset:35840
	ds_read_b128 v[194:197], v210 offset:36864
	ds_read_b128 v[198:201], v210 offset:37888
	ds_read_b128 v[202:205], v210 offset:38912
	ds_read_b128 v[212:215], v210 offset:39936
	s_nop 0
	global_load_lds_dwordx4 v1, s[4:5]
	s_mov_b32 m0, s21
	s_nop 0
	global_load_lds_dwordx4 v164, s[4:5]
	s_waitcnt vmcnt(8)
	s_waitcnt lgkmcnt(0)
	s_barrier
	s_setprio 1
	s_waitcnt lgkmcnt(0)
	v_mfma_f32_16x16x32_bf16 v[142:145], v[74:77], v[248:251], v[142:145]
	v_mfma_f32_16x16x32_bf16 v[142:145], v[78:81], v[252:255], v[142:145]
	v_mfma_f32_16x16x32_bf16 v[134:137], v[74:77], v[186:189], v[134:137]
	v_mfma_f32_16x16x32_bf16 v[134:137], v[78:81], v[190:193], v[134:137]
	v_mfma_f32_16x16x32_bf16 v[126:129], v[74:77], v[194:197], v[126:129]
	v_mfma_f32_16x16x32_bf16 v[126:129], v[78:81], v[198:201], v[126:129]
	v_mfma_f32_16x16x32_bf16 v[118:121], v[74:77], v[202:205], v[118:121]
	v_mfma_f32_16x16x32_bf16 v[118:121], v[78:81], v[212:215], v[118:121]
	v_mfma_f32_16x16x32_bf16 v[138:141], v[98:101], v[248:251], v[138:141]
	v_mfma_f32_16x16x32_bf16 v[138:141], v[102:105], v[252:255], v[138:141]
	v_mfma_f32_16x16x32_bf16 v[130:133], v[98:101], v[186:189], v[130:133]
	v_mfma_f32_16x16x32_bf16 v[130:133], v[102:105], v[190:193], v[130:133]
	v_mfma_f32_16x16x32_bf16 v[122:125], v[98:101], v[194:197], v[122:125]
	v_mfma_f32_16x16x32_bf16 v[122:125], v[102:105], v[198:201], v[122:125]
	v_mfma_f32_16x16x32_bf16 v[114:117], v[98:101], v[202:205], v[114:117]
	v_mfma_f32_16x16x32_bf16 v[114:117], v[102:105], v[212:215], v[114:117]
	s_setprio 0
	s_setprio 1
	v_mfma_f32_16x16x32_bf16 v[70:73], v[146:149], v[248:251], v[70:73]
	v_mfma_f32_16x16x32_bf16 v[70:73], v[150:153], v[252:255], v[70:73]
	v_mfma_f32_16x16x32_bf16 v[62:65], v[146:149], v[186:189], v[62:65]
	v_mfma_f32_16x16x32_bf16 v[62:65], v[150:153], v[190:193], v[62:65]
	v_mfma_f32_16x16x32_bf16 v[54:57], v[146:149], v[194:197], v[54:57]
	v_mfma_f32_16x16x32_bf16 v[54:57], v[150:153], v[198:201], v[54:57]
	v_mfma_f32_16x16x32_bf16 v[46:49], v[146:149], v[202:205], v[46:49]
	v_mfma_f32_16x16x32_bf16 v[46:49], v[150:153], v[212:215], v[46:49]
	v_mfma_f32_16x16x32_bf16 v[66:69], v[154:157], v[248:251], v[66:69]
	v_mfma_f32_16x16x32_bf16 v[66:69], v[158:161], v[252:255], v[66:69]
	v_mfma_f32_16x16x32_bf16 v[58:61], v[154:157], v[186:189], v[58:61]
	v_mfma_f32_16x16x32_bf16 v[58:61], v[158:161], v[190:193], v[58:61]
	v_mfma_f32_16x16x32_bf16 v[50:53], v[154:157], v[194:197], v[50:53]
	v_mfma_f32_16x16x32_bf16 v[50:53], v[158:161], v[198:201], v[50:53]
	v_mfma_f32_16x16x32_bf16 v[42:45], v[154:157], v[202:205], v[42:45]
	v_mfma_f32_16x16x32_bf16 v[42:45], v[158:161], v[212:215], v[42:45]
	s_setprio 0
	s_barrier
; #define PG8_STAGE(bufoff, gbase, voff) do { const char* gb_ = (const char*)(gbase); asm volatile("" : "+s"(gb_)); _Pragma("unroll") for (int _i = 0; _i < 2; ++_i) { unsigned vo_ = (voff)[_i]; asm volatile("" : "+v"(vo_));        \
;         __builtin_amdgcn_global_load_lds((const unsigned*)(gb_ + vo_), (PG8_LAS unsigned*)(lds + (bufoff) + ldsw + _i * 8192), 16, 0, 0); } } while (0)
; #define PG8_LDA(dst, b, h) do { _Pragma("unroll") for (int m = 0; m < 4; ++m) _Pragma("unroll") for (int k = 0; k < 2; ++k) dst[m][k] = *(const PG8_LAS bf16x8*)(lds + PG8_SA(b, h) + aoff + m * 2048 + k * 1024); } while (0)
;     __device__ __forceinline__ void operator()(const f32x4 (&acc)[2][2][4][2], const Unit& u, int wr, int wc, int fr, int fq) const {
;         const int row0 = u.pm * BM + wr * 64 + fr, col0 = u.pn * BM + wc * 32 + 8 * fq, b = (u.pm * BM) / rows_per_batch;
;         const float* g = gate + (size_t)b * gate_bstride + col0;
;         float ssq[2][4];
; #pragma unroll
;         for (int ai = 0; ai < 2; ++ai)
; #pragma unroll
;             for (int m = 0; m < 4; ++m) ssq[ai][m] = 0.f;
;         f32x4 gv[2][2], Gv[2][2];
; #pragma unroll
;         for (int bj = 0; bj < 2; ++bj) { gv[bj][0] = *(const f32x4*)(g + bj * HALF); gv[bj][1] = *(const f32x4*)(g + bj * HALF + 4); Gv[bj][0] = (f32x4){0.f, 0.f, 0.f, 0.f}; Gv[bj][1] = (f32x4){0.f, 0.f, 0.f, 0.f};
;             if (Hn) { const float* sc = scnext + (size_t)b * gate_bstride + col0 + bj * HALF;
;                 Gv[bj][0] = *(const f32x4*)(gnext + col0 + bj * HALF) * (1.0f + *(const f32x4*)(sc)); Gv[bj][1] = *(const f32x4*)(gnext + col0 + bj * HALF + 4) * (1.0f + *(const f32x4*)(sc + 4)); } }
; template <class Epi, class Sched, bool ALIGN_EPI = false, bool SP2 = false>
; __device__ __forceinline__ void gemm_phase(PG8_LAS unsigned char* lds, const Gemm g, const Sched& S, const Epi& E) {
;     ...
;             PG8_LDB(B0, 1, 0); PG8_LDB(B1, 1, 1); PG8_SCHED; PG8_LDA(At, 1, 0); PG8_STAGE(PG8_SA(0, 1), a2 + hstep, voffA);
;             PG8_WAIT_V(8); PG8_WAIT_L(0); PG8_BAR; PG8_MMA(0, 0, At, B0); PG8_MMA(0, 1, At, B1); PG8_BAR; PG8_SCHED;
;             PG8_LDA(At, 1, 1); PG8_STAGE(PG8_SB(1, 0), b3, voffB); PG8_STAGE(PG8_SB(1, 1), b3 + hstep, voffB); PG8_STAGE(PG8_SA(1, 0), a3, voffA);
;             PG8_WAIT_V(8); PG8_WAIT_L(0); PG8_BAR; PG8_MMA(1, 0, At, B0); PG8_MMA(1, 1, At, B1); PG8_BAR; PG8_SCHED;
	s_add_u32 s4, s10, 0x80
	s_addc_u32 s5, s11, 0
	s_add_i32 s12, s56, s17
	ds_read_b128 v[248:251], v210 offset:49152
	ds_read_b128 v[252:255], v210 offset:50176
	ds_read_b128 v[186:189], v210 offset:51200
	ds_read_b128 v[190:193], v210 offset:52224
	ds_read_b128 v[194:197], v210 offset:53248
	ds_read_b128 v[198:201], v210 offset:54272
	ds_read_b128 v[202:205], v210 offset:55296
	ds_read_b128 v[212:215], v210 offset:56320
	s_mov_b32 m0, s12
	s_nop 0
	global_load_lds_dwordx4 v162, s[4:5]
	s_add_i32 m0, s12, 0x2000
	s_nop 0
	global_load_lds_dwordx4 v206, s[4:5]
	s_add_u32 s4, s10, 0x80080
	s_addc_u32 s5, s11, 0
	s_add_i32 s10, s57, s17
	s_mov_b32 m0, s10
	s_nop 0
	global_load_lds_dwordx4 v162, s[4:5]
	s_add_i32 m0, s10, 0x2000
	s_nop 0
	global_load_lds_dwordx4 v206, s[4:5]
	s_mov_b32 m0, s26
	s_nop 0
	global_load_lds_dwordx4 v1, s[8:9]
	s_mov_b32 m0, s27
	s_nop 0
	global_load_lds_dwordx4 v164, s[8:9]
	s_waitcnt vmcnt(8)
	s_waitcnt lgkmcnt(0)
	s_barrier
	s_setprio 1
	s_waitcnt lgkmcnt(0)
	v_mfma_f32_16x16x32_bf16 v[110:113], v[74:77], v[248:251], v[110:113]
	v_mfma_f32_16x16x32_bf16 v[110:113], v[78:81], v[252:255], v[110:113]
	v_mfma_f32_16x16x32_bf16 v[94:97], v[74:77], v[186:189], v[94:97]
	v_mfma_f32_16x16x32_bf16 v[94:97], v[78:81], v[190:193], v[94:97]
	v_mfma_f32_16x16x32_bf16 v[86:89], v[74:77], v[194:197], v[86:89]
	v_mfma_f32_16x16x32_bf16 v[86:89], v[78:81], v[198:201], v[86:89]
	v_mfma_f32_16x16x32_bf16 v[26:29], v[74:77], v[202:205], v[26:29]
	v_mfma_f32_16x16x32_bf16 v[78:81], v[78:81], v[212:215], v[26:29]
	v_mfma_f32_16x16x32_bf16 v[106:109], v[98:101], v[248:251], v[106:109]
	v_mfma_f32_16x16x32_bf16 v[106:109], v[102:105], v[252:255], v[106:109]
	v_mfma_f32_16x16x32_bf16 v[90:93], v[98:101], v[186:189], v[90:93]
	v_mfma_f32_16x16x32_bf16 v[90:93], v[102:105], v[190:193], v[90:93]
	v_mfma_f32_16x16x32_bf16 v[82:85], v[98:101], v[194:197], v[82:85]
	v_mfma_f32_16x16x32_bf16 v[82:85], v[102:105], v[198:201], v[82:85]
	v_mfma_f32_16x16x32_bf16 v[26:29], v[98:101], v[202:205], v[30:33]
	v_mfma_f32_16x16x32_bf16 v[74:77], v[102:105], v[212:215], v[26:29]
	s_setprio 0
	s_setprio 1
	v_mfma_f32_16x16x32_bf16 v[26:29], v[146:149], v[248:251], v[38:41]
	v_mfma_f32_16x16x32_bf16 v[38:41], v[150:153], v[252:255], v[26:29]
	v_mfma_f32_16x16x32_bf16 v[22:25], v[146:149], v[186:189], v[22:25]
	v_mfma_f32_16x16x32_bf16 v[22:25], v[150:153], v[190:193], v[22:25]
	v_mfma_f32_16x16x32_bf16 v[14:17], v[146:149], v[194:197], v[14:17]
	v_mfma_f32_16x16x32_bf16 v[14:17], v[150:153], v[198:201], v[14:17]
	v_mfma_f32_16x16x32_bf16 v[6:9], v[146:149], v[202:205], v[6:9]
	v_mfma_f32_16x16x32_bf16 v[6:9], v[150:153], v[212:215], v[6:9]
	v_mfma_f32_16x16x32_bf16 v[26:29], v[154:157], v[248:251], v[34:37]
	v_mfma_f32_16x16x32_bf16 v[34:37], v[158:161], v[252:255], v[26:29]
	v_mfma_f32_16x16x32_bf16 v[18:21], v[154:157], v[186:189], v[18:21]
	v_mfma_f32_16x16x32_bf16 v[18:21], v[158:161], v[190:193], v[18:21]
	v_mfma_f32_16x16x32_bf16 v[10:13], v[154:157], v[194:197], v[10:13]
	v_mfma_f32_16x16x32_bf16 v[10:13], v[158:161], v[198:201], v[10:13]
	v_mfma_f32_16x16x32_bf16 v[2:5], v[154:157], v[202:205], v[2:5]
	v_mfma_f32_16x16x32_bf16 v[2:5], v[158:161], v[212:215], v[2:5]
	s_setprio 0
	s_barrier
	s_add_i32 s51, s51, 2
	s_add_u32 s40, s40, 0x100
	s_addc_u32 s49, s49, 0
	s_cmp_gt_u32 s51, 29
	s_mov_b64 s[4:5], s[6:7]
	s_cbranch_scc0 .LBB0_555
	s_ashr_i32 s4, s29, 31
	s_lshr_b32 s4, s4, 27
	s_add_i32 s4, s29, s4
	s_ashr_i32 s4, s4, 5
	v_lshl_or_b32 v148, s33, 8, v209
	s_mul_i32 s7, s4, 0xc000
	v_ashrrev_i32_e32 v149, 31, v148
	s_mul_hi_i32 s6, s4, 0xc000
	s_add_u32 s4, s22, s7
	s_addc_u32 s5, s23, s6
	v_lshlrev_b64 v[26:27], 2, v[148:149]
	v_lshl_add_u64 v[146:147], s[4:5], 0, v[26:27]
	s_add_u32 s4, s24, s7
	s_addc_u32 s5, s25, s6
	v_lshl_add_u64 v[160:161], s[4:5], 0, v[26:27]
	v_lshl_add_u64 v[178:179], s[46:47], 0, v[26:27]
	global_load_dwordx4 v[98:101], v[146:147], off offset:16
	global_load_dwordx4 v[102:105], v[146:147], off
	global_load_dwordx4 v[26:29], v[178:179], off offset:16
	global_load_dwordx4 v[30:33], v[178:179], off
	global_load_dwordx4 v[150:153], v[160:161], off offset:16
	global_load_dwordx4 v[154:157], v[160:161], off
	s_mov_b64 s[4:5], 0x40000
	s_waitcnt vmcnt(0)
	v_pk_mul_f32 v[188:189], v[140:141], v[100:101]
	v_pk_mul_f32 v[142:143], v[142:143], v[102:103]
	v_pk_mul_f32 v[144:145], v[144:145], v[104:105]
	v_pk_mul_f32 v[140:141], v[138:139], v[98:99]
	v_pk_mul_f32 v[136:137], v[136:137], v[104:105]
	v_pk_add_f32 v[156:157], v[156:157], 1.0 op_sel_hi:[1,0]
	v_pk_add_f32 v[154:155], v[154:155], 1.0 op_sel_hi:[1,0]
	v_pk_mul_f32 v[198:199], v[32:33], v[156:157]
	v_pk_mul_f32 v[200:201], v[30:31], v[154:155]
	v_pk_add_f32 v[30:31], v[152:153], 1.0 op_sel_hi:[1,0]
	v_pk_add_f32 v[32:33], v[150:151], 1.0 op_sel_hi:[1,0]
	v_pk_mul_f32 v[202:203], v[28:29], v[30:31]
	v_pk_mul_f32 v[204:205], v[26:27], v[32:33]
	global_load_dwordx4 v[26:29], v[146:147], off offset:528
	global_load_dwordx4 v[30:33], v[146:147], off offset:512
	global_load_dwordx4 v[156:159], v[178:179], off offset:528
	global_load_dwordx4 v[152:155], v[178:179], off offset:512
	s_nop 0
	global_load_dwordx4 v[178:181], v[160:161], off offset:528
	global_load_dwordx4 v[182:185], v[160:161], off offset:512
	v_pk_mul_f32 v[134:135], v[134:135], v[102:103]
	v_pk_mul_f32 v[130:131], v[130:131], v[98:99]
	v_pk_mul_f32 v[132:133], v[132:133], v[100:101]
	v_pk_mul_f32 v[128:129], v[128:129], v[104:105]
	v_pk_mul_f32 v[126:127], v[126:127], v[102:103]
	v_pk_mul_f32 v[122:123], v[122:123], v[98:99]
	v_pk_mul_f32 v[124:125], v[124:125], v[100:101]
	v_pk_mul_f32 v[120:121], v[120:121], v[104:105]
	v_pk_mul_f32 v[118:119], v[118:119], v[102:103]
	v_pk_mul_f32 v[114:115], v[114:115], v[98:99]
	v_pk_mul_f32 v[116:117], v[116:117], v[100:101]
	v_pk_mul_f32 v[112:113], v[112:113], v[104:105]
	v_pk_mul_f32 v[110:111], v[110:111], v[102:103]
	v_pk_mul_f32 v[106:107], v[106:107], v[98:99]
	v_pk_mul_f32 v[108:109], v[108:109], v[100:101]
	v_pk_mul_f32 v[96:97], v[96:97], v[104:105]
	v_pk_mul_f32 v[94:95], v[94:95], v[102:103]
	v_pk_mul_f32 v[90:91], v[90:91], v[98:99]
	v_pk_mul_f32 v[92:93], v[92:93], v[100:101]
	v_pk_mul_f32 v[88:89], v[88:89], v[104:105]
	v_pk_mul_f32 v[86:87], v[86:87], v[102:103]
	v_pk_mul_f32 v[82:83], v[82:83], v[98:99]
	v_pk_mul_f32 v[84:85], v[84:85], v[100:101]
	v_pk_mul_f32 v[80:81], v[80:81], v[104:105]
	v_pk_mul_f32 v[78:79], v[78:79], v[102:103]
	v_pk_mul_f32 v[74:75], v[74:75], v[98:99]
	v_pk_mul_f32 v[76:77], v[76:77], v[100:101]
	s_waitcnt vmcnt(5)
;     __device__ __forceinline__ void operator()(const f32x4 (&acc)[2][2][4][2], const Unit& u, int wr, int wc, int fr, int fq) const {
;     ...
;         for (int bj = 0; bj < 2; ++bj) {
;             const f32x4 g0 = gv[bj][0], g1 = gv[bj][1], G0 = Gv[bj][0], G1 = Gv[bj][1];
; #pragma unroll
;             for (int ai = 0; ai < 2; ++ai)
; #pragma unroll
;                 for (int m = 0; m < 4; ++m) { const size_t off = (size_t)(row0 + ai * HALF + m * 16) * 2048 + col0 + bj * HALF;
;                     f32x4 x0 = __builtin_nontemporal_load((const f32x4*)(base + off)), x1 = __builtin_nontemporal_load((const f32x4*)(base + off + 4));
;                     if constexpr (HAS_DIN) { const u32x4 dw = __builtin_nontemporal_load((const u32x4*)(dbuf + off));
;                         x0 += (f32x4){__builtin_bit_cast(float, dw.x << 16), __builtin_bit_cast(float, dw.x & 0xffff0000u), __builtin_bit_cast(float, dw.y << 16), __builtin_bit_cast(float, dw.y & 0xffff0000u)};
;                         x1 += (f32x4){__builtin_bit_cast(float, dw.z << 16), __builtin_bit_cast(float, dw.z & 0xffff0000u), __builtin_bit_cast(float, dw.w << 16), __builtin_bit_cast(float, dw.w & 0xffff0000u)}; }
;                     f32x4 o0, o1;
;                     if constexpr (OUT_DELTA) { const f32x4 d0 = g0 * acc[ai][bj][m][0], d1 = g1 * acc[ai][bj][m][1];
;                         u32x4 w; w.x = cvt_pk_bf16(d0[0], d0[1]); w.y = cvt_pk_bf16(d0[2], d0[3]); w.z = cvt_pk_bf16(d1[0], d1[1]); w.w = cvt_pk_bf16(d1[2], d1[3]);
;                         *(u32x4*)(dbuf + off) = w;
;                         o0 = x0 + (f32x4){__builtin_bit_cast(float, w.x << 16), __builtin_bit_cast(float, w.x & 0xffff0000u), __builtin_bit_cast(float, w.y << 16), __builtin_bit_cast(float, w.y & 0xffff0000u)};
;                         o1 = x1 + (f32x4){__builtin_bit_cast(float, w.z << 16), __builtin_bit_cast(float, w.z & 0xffff0000u), __builtin_bit_cast(float, w.w << 16), __builtin_bit_cast(float, w.w & 0xffff0000u)}; }
;                     else { o0 = x0 + g0 * acc[ai][bj][m][0]; o1 = x1 + g1 * acc[ai][bj][m][1]; *(f32x4*)(out + off) = o0; *(f32x4*)(out + off + 4) = o1; }
;                     if (Hn) { const f32x4 h0 = o0 * G0, h1 = o1 * G1;
;                         u32x4 w; w.x = cvt_pk_bf16(h0[0], h0[1]); w.y = cvt_pk_bf16(h0[2], h0[3]); w.z = cvt_pk_bf16(h1[0], h1[1]); w.w = cvt_pk_bf16(h1[2], h1[3]);
	v_pk_mul_f32 v[58:59], v[58:59], v[26:27]
	s_waitcnt vmcnt(4)
	v_pk_mul_f32 v[72:73], v[72:73], v[32:33]
	v_pk_mul_f32 v[70:71], v[70:71], v[30:31]
	v_pk_mul_f32 v[64:65], v[64:65], v[32:33]
	v_pk_mul_f32 v[62:63], v[62:63], v[30:31]
	s_waitcnt vmcnt(0)
	v_pk_add_f32 v[146:147], v[184:185], 1.0 op_sel_hi:[1,0]
	v_pk_add_f32 v[160:161], v[182:183], 1.0 op_sel_hi:[1,0]
	v_pk_mul_f32 v[150:151], v[154:155], v[146:147]
	v_pk_add_f32 v[146:147], v[180:181], 1.0 op_sel_hi:[1,0]
	v_pk_mul_f32 v[152:153], v[152:153], v[160:161]
	v_pk_mul_f32 v[154:155], v[158:159], v[146:147]
	v_lshl_add_u32 v146, s29, 8, v207
	v_ashrrev_i32_e32 v147, 31, v146
	v_lshlrev_b64 v[184:185], 11, v[146:147]
	v_lshl_add_u64 v[186:187], v[184:185], 0, v[148:149]
	v_pk_add_f32 v[160:161], v[178:179], 1.0 op_sel_hi:[1,0]
	v_lshl_add_u64 v[178:179], v[186:187], 2, s[44:45]
	v_pk_mul_f32 v[156:157], v[156:157], v[160:161]
	global_load_dwordx4 v[158:161], v[178:179], off nt
	global_load_dwordx4 v[180:183], v[178:179], off offset:16 nt
	v_cvt_pk_bf16_f32 v138, v142, v143
	v_lshlrev_b64 v[142:143], 1, v[186:187]
	v_cvt_pk_bf16_f32 v139, v144, v145
	v_cvt_pk_bf16_f32 v140, v140, v141
	v_cvt_pk_bf16_f32 v141, v188, v189
	v_lshl_add_u64 v[144:145], s[90:91], 0, v[142:143]
	global_store_dwordx4 v[144:145], v[138:141], off
	v_lshlrev_b32_e32 v144, 16, v140
	v_and_b32_e32 v145, 0xffff0000, v140
	v_lshlrev_b32_e32 v140, 16, v141
	v_and_b32_e32 v141, 0xffff0000, v141
	v_lshl_add_u64 v[142:143], s[96:97], 0, v[142:143]
	v_pk_mul_f32 v[60:61], v[60:61], v[28:29]
	v_pk_mul_f32 v[56:57], v[56:57], v[32:33]
	v_pk_mul_f32 v[54:55], v[54:55], v[30:31]
	v_pk_mul_f32 v[50:51], v[50:51], v[26:27]
	v_pk_mul_f32 v[52:53], v[52:53], v[28:29]
	v_pk_mul_f32 v[48:49], v[48:49], v[32:33]
	v_pk_mul_f32 v[46:47], v[46:47], v[30:31]
	v_pk_mul_f32 v[42:43], v[42:43], v[26:27]
	v_pk_mul_f32 v[44:45], v[44:45], v[28:29]
	v_pk_mul_f32 v[40:41], v[40:41], v[32:33]
	v_pk_mul_f32 v[38:39], v[38:39], v[30:31]
	v_pk_mul_f32 v[34:35], v[34:35], v[26:27]
	v_pk_mul_f32 v[36:37], v[36:37], v[28:29]
	v_pk_mul_f32 v[24:25], v[24:25], v[32:33]
	v_pk_mul_f32 v[22:23], v[22:23], v[30:31]
	v_pk_mul_f32 v[18:19], v[18:19], v[26:27]
	v_pk_mul_f32 v[20:21], v[20:21], v[28:29]
	v_pk_mul_f32 v[16:17], v[16:17], v[32:33]
	v_pk_mul_f32 v[14:15], v[14:15], v[30:31]
	v_pk_mul_f32 v[10:11], v[10:11], v[26:27]
	v_pk_mul_f32 v[12:13], v[12:13], v[28:29]
	v_pk_mul_f32 v[8:9], v[8:9], v[32:33]
	v_pk_mul_f32 v[6:7], v[6:7], v[30:31]
	v_pk_mul_f32 v[2:3], v[2:3], v[26:27]
	v_pk_mul_f32 v[4:5], v[4:5], v[28:29]
	s_waitcnt vmcnt(1)
	v_pk_add_f32 v[182:183], v[182:183], v[140:141]
	v_lshlrev_b32_e32 v140, 16, v138
	v_and_b32_e32 v141, 0xffff0000, v138
	v_lshlrev_b32_e32 v138, 16, v139
	v_and_b32_e32 v139, 0xffff0000, v139
	v_pk_add_f32 v[158:159], v[158:159], v[140:141]
	v_pk_add_f32 v[160:161], v[160:161], v[138:139]
	v_pk_mul_f32 v[138:139], v[200:201], v[158:159]
	v_pk_add_f32 v[144:145], v[180:181], v[144:145]
	v_pk_mul_f32 v[140:141], v[198:199], v[160:161]
	v_cvt_pk_bf16_f32 v138, v138, v139
	v_pk_mul_f32 v[180:181], v[202:203], v[182:183]
	v_cvt_pk_bf16_f32 v139, v140, v141
	v_pk_mul_f32 v[186:187], v[204:205], v[144:145]
	s_nop 0
	v_cvt_pk_bf16_f32 v140, v186, v187
	v_cvt_pk_bf16_f32 v141, v180, v181
	global_store_dwordx4 v[142:143], v[138:141], off
	s_nop 1
	v_mul_f32_e32 v138, v159, v159
	v_mul_f32_e32 v139, v161, v161
	v_fmac_f32_e32 v138, v158, v158
	v_fmac_f32_e32 v139, v160, v160
	v_add_f32_e32 v138, v138, v139
	v_mul_f32_e32 v139, v145, v145
	v_mul_f32_e32 v140, v183, v183
	v_fmac_f32_e32 v139, v144, v144
	v_fmac_f32_e32 v140, v182, v182
	v_add_f32_e32 v139, v139, v140
	v_add_f32_e32 v211, v138, v139
	v_or_b32_e32 v138, 16, v146
	v_ashrrev_i32_e32 v139, 31, v138
	v_lshlrev_b64 v[140:141], 11, v[138:139]
	v_lshl_add_u64 v[180:181], v[140:141], 0, v[148:149]
	v_lshl_add_u64 v[138:139], v[180:181], 2, s[44:45]
	global_load_dwordx4 v[142:145], v[138:139], off nt
	global_load_dwordx4 v[158:161], v[138:139], off offset:16 nt
	v_lshlrev_b64 v[180:181], 1, v[180:181]
	v_cvt_pk_bf16_f32 v134, v134, v135
	v_cvt_pk_bf16_f32 v135, v136, v137
	v_cvt_pk_bf16_f32 v136, v130, v131
	v_cvt_pk_bf16_f32 v137, v132, v133
	v_lshl_add_u64 v[130:131], s[90:91], 0, v[180:181]
	global_store_dwordx4 v[130:131], v[134:137], off
	v_lshlrev_b32_e32 v132, 16, v136
	v_and_b32_e32 v133, 0xffff0000, v136
	v_lshlrev_b32_e32 v130, 16, v137
	v_and_b32_e32 v131, 0xffff0000, v137
	v_lshlrev_b32_e32 v136, 16, v134
	v_and_b32_e32 v137, 0xffff0000, v134
	v_lshlrev_b32_e32 v134, 16, v135
	v_and_b32_e32 v135, 0xffff0000, v135
	s_waitcnt vmcnt(2)
	v_pk_add_f32 v[134:135], v[144:145], v[134:135]
	s_waitcnt vmcnt(1)
	v_pk_add_f32 v[130:131], v[160:161], v[130:131]
	v_pk_add_f32 v[136:137], v[142:143], v[136:137]
	v_pk_add_f32 v[132:133], v[158:159], v[132:133]
	v_pk_mul_f32 v[144:145], v[198:199], v[134:135]
	v_pk_mul_f32 v[142:143], v[200:201], v[136:137]
	v_pk_mul_f32 v[158:159], v[202:203], v[130:131]
	v_pk_mul_f32 v[160:161], v[204:205], v[132:133]
	v_cvt_pk_bf16_f32 v142, v142, v143
	v_cvt_pk_bf16_f32 v143, v144, v145
	s_nop 0
	v_cvt_pk_bf16_f32 v144, v160, v161
	v_cvt_pk_bf16_f32 v145, v158, v159
	v_lshl_add_u64 v[158:159], s[96:97], 0, v[180:181]
	global_store_dwordx4 v[158:159], v[142:145], off
	s_nop 1
	v_or_b32_e32 v142, 32, v146
	v_ashrrev_i32_e32 v143, 31, v142
	v_lshlrev_b64 v[144:145], 11, v[142:143]
	v_lshl_add_u64 v[186:187], v[144:145], 0, v[148:149]
	v_lshl_add_u64 v[142:143], v[186:187], 2, s[44:45]
	global_load_dwordx4 v[158:161], v[142:143], off nt
	global_load_dwordx4 v[180:183], v[142:143], off offset:16 nt
	v_lshlrev_b64 v[186:187], 1, v[186:187]
	v_cvt_pk_bf16_f32 v126, v126, v127
	v_cvt_pk_bf16_f32 v127, v128, v129
	v_cvt_pk_bf16_f32 v128, v122, v123
	v_cvt_pk_bf16_f32 v129, v124, v125
	v_lshl_add_u64 v[122:123], s[90:91], 0, v[186:187]
	global_store_dwordx4 v[122:123], v[126:129], off
	v_lshlrev_b32_e32 v124, 16, v128
	v_and_b32_e32 v125, 0xffff0000, v128
	v_lshlrev_b32_e32 v122, 16, v129
	v_and_b32_e32 v123, 0xffff0000, v129
	v_lshlrev_b32_e32 v128, 16, v126
	v_and_b32_e32 v129, 0xffff0000, v126
	v_lshlrev_b32_e32 v126, 16, v127
	v_and_b32_e32 v127, 0xffff0000, v127
	s_waitcnt vmcnt(2)
; __device__ __forceinline__ unsigned cvt_pk_bf16(float lo, float hi) { unsigned r; asm volatile("v_cvt_pk_bf16_f32 %0, %1, %2" : "=v"(r) : "v"(lo), "v"(hi)); return r; }
;     __device__ __forceinline__ void operator()(const f32x4 (&acc)[2][2][4][2], const Unit& u, int wr, int wc, int fr, int fq) const {
;     ...
;                 for (int m = 0; m < 4; ++m) { const size_t off = (size_t)(row0 + ai * HALF + m * 16) * 2048 + col0 + bj * HALF;
;                     f32x4 x0 = __builtin_nontemporal_load((const f32x4*)(base + off)), x1 = __builtin_nontemporal_load((const f32x4*)(base + off + 4));
;                     if constexpr (HAS_DIN) { const u32x4 dw = __builtin_nontemporal_load((const u32x4*)(dbuf + off));
;                         x0 += (f32x4){__builtin_bit_cast(float, dw.x << 16), __builtin_bit_cast(float, dw.x & 0xffff0000u), __builtin_bit_cast(float, dw.y << 16), __builtin_bit_cast(float, dw.y & 0xffff0000u)};
;                         x1 += (f32x4){__builtin_bit_cast(float, dw.z << 16), __builtin_bit_cast(float, dw.z & 0xffff0000u), __builtin_bit_cast(float, dw.w << 16), __builtin_bit_cast(float, dw.w & 0xffff0000u)}; }
;                     f32x4 o0, o1;
;                     if constexpr (OUT_DELTA) { const f32x4 d0 = g0 * acc[ai][bj][m][0], d1 = g1 * acc[ai][bj][m][1];
;                         u32x4 w; w.x = cvt_pk_bf16(d0[0], d0[1]); w.y = cvt_pk_bf16(d0[2], d0[3]); w.z = cvt_pk_bf16(d1[0], d1[1]); w.w = cvt_pk_bf16(d1[2], d1[3]);
;                         *(u32x4*)(dbuf + off) = w;
;                         o0 = x0 + (f32x4){__builtin_bit_cast(float, w.x << 16), __builtin_bit_cast(float, w.x & 0xffff0000u), __builtin_bit_cast(float, w.y << 16), __builtin_bit_cast(float, w.y & 0xffff0000u)};
;                         o1 = x1 + (f32x4){__builtin_bit_cast(float, w.z << 16), __builtin_bit_cast(float, w.z & 0xffff0000u), __builtin_bit_cast(float, w.w << 16), __builtin_bit_cast(float, w.w & 0xffff0000u)}; }
;                     else { o0 = x0 + g0 * acc[ai][bj][m][0]; o1 = x1 + g1 * acc[ai][bj][m][1]; *(f32x4*)(out + off) = o0; *(f32x4*)(out + off + 4) = o1; }
;                     if (Hn) { const f32x4 h0 = o0 * G0, h1 = o1 * G1;
;                         u32x4 w; w.x = cvt_pk_bf16(h0[0], h0[1]); w.y = cvt_pk_bf16(h0[2], h0[3]); w.z = cvt_pk_bf16(h1[0], h1[1]); w.w = cvt_pk_bf16(h1[2], h1[3]);
;                         *(u32x4*)(Hn + off) = w;
	v_pk_add_f32 v[126:127], v[160:161], v[126:127]
	s_waitcnt vmcnt(1)
	v_pk_add_f32 v[122:123], v[182:183], v[122:123]
	v_pk_add_f32 v[128:129], v[158:159], v[128:129]
	v_pk_add_f32 v[124:125], v[180:181], v[124:125]
	v_pk_mul_f32 v[160:161], v[198:199], v[126:127]
	v_pk_mul_f32 v[158:159], v[200:201], v[128:129]
	v_pk_mul_f32 v[180:181], v[202:203], v[122:123]
	v_pk_mul_f32 v[182:183], v[204:205], v[124:125]
	v_cvt_pk_bf16_f32 v158, v158, v159
	v_cvt_pk_bf16_f32 v159, v160, v161
	s_nop 0
	v_cvt_pk_bf16_f32 v160, v182, v183
	v_cvt_pk_bf16_f32 v161, v180, v181
	v_lshl_add_u64 v[180:181], s[96:97], 0, v[186:187]
	global_store_dwordx4 v[180:181], v[158:161], off
	s_nop 1
	v_or_b32_e32 v158, 48, v146
	v_ashrrev_i32_e32 v159, 31, v158
	v_lshlrev_b64 v[160:161], 11, v[158:159]
	v_lshl_add_u64 v[190:191], v[160:161], 0, v[148:149]
	v_lshl_add_u64 v[158:159], v[190:191], 2, s[44:45]
	global_load_dwordx4 v[180:183], v[158:159], off nt
	global_load_dwordx4 v[186:189], v[158:159], off offset:16 nt
	v_lshlrev_b64 v[190:191], 1, v[190:191]
	v_cvt_pk_bf16_f32 v118, v118, v119
	v_cvt_pk_bf16_f32 v119, v120, v121
	v_cvt_pk_bf16_f32 v120, v114, v115
	v_cvt_pk_bf16_f32 v121, v116, v117
	v_lshl_add_u64 v[114:115], s[90:91], 0, v[190:191]
	global_store_dwordx4 v[114:115], v[118:121], off
	v_lshlrev_b32_e32 v116, 16, v120
	v_and_b32_e32 v117, 0xffff0000, v120
	v_lshlrev_b32_e32 v114, 16, v121
	v_and_b32_e32 v115, 0xffff0000, v121
	v_lshlrev_b32_e32 v120, 16, v118
	v_and_b32_e32 v121, 0xffff0000, v118
	v_lshlrev_b32_e32 v118, 16, v119
	v_and_b32_e32 v119, 0xffff0000, v119
	s_waitcnt vmcnt(2)
	v_pk_add_f32 v[118:119], v[182:183], v[118:119]
	s_waitcnt vmcnt(1)
	v_pk_add_f32 v[114:115], v[188:189], v[114:115]
	v_pk_add_f32 v[120:121], v[180:181], v[120:121]
	v_pk_add_f32 v[116:117], v[186:187], v[116:117]
	v_pk_mul_f32 v[182:183], v[198:199], v[118:119]
	v_pk_mul_f32 v[180:181], v[200:201], v[120:121]
	v_pk_mul_f32 v[186:187], v[202:203], v[114:115]
	v_pk_mul_f32 v[188:189], v[204:205], v[116:117]
	v_cvt_pk_bf16_f32 v180, v180, v181
	v_cvt_pk_bf16_f32 v181, v182, v183
	s_nop 0
	v_cvt_pk_bf16_f32 v182, v188, v189
	v_cvt_pk_bf16_f32 v183, v186, v187
	v_lshl_add_u64 v[186:187], s[96:97], 0, v[190:191]
	global_store_dwordx4 v[186:187], v[180:183], off
	s_nop 1
	v_lshl_add_u64 v[182:183], v[184:185], 0, s[4:5]
	v_lshl_add_u64 v[194:195], v[182:183], 0, v[148:149]
	v_lshl_add_u64 v[180:181], v[194:195], 2, s[44:45]
	global_load_dwordx4 v[186:189], v[180:181], off nt
	global_load_dwordx4 v[190:193], v[180:181], off offset:16 nt
	v_lshlrev_b64 v[194:195], 1, v[194:195]
	v_cvt_pk_bf16_f32 v110, v110, v111
	v_cvt_pk_bf16_f32 v111, v112, v113
	v_cvt_pk_bf16_f32 v112, v106, v107
	v_cvt_pk_bf16_f32 v113, v108, v109
	v_lshl_add_u64 v[106:107], s[90:91], 0, v[194:195]
	global_store_dwordx4 v[106:107], v[110:113], off
	v_lshlrev_b32_e32 v108, 16, v112
	v_and_b32_e32 v109, 0xffff0000, v112
	v_lshlrev_b32_e32 v106, 16, v113
	v_and_b32_e32 v107, 0xffff0000, v113
	v_lshlrev_b32_e32 v112, 16, v110
	v_and_b32_e32 v113, 0xffff0000, v110
	v_lshlrev_b32_e32 v110, 16, v111
	v_and_b32_e32 v111, 0xffff0000, v111
	s_mov_b64 s[4:5], 0x48000
	s_waitcnt vmcnt(2)
	v_pk_add_f32 v[110:111], v[188:189], v[110:111]
	s_waitcnt vmcnt(1)
	v_pk_add_f32 v[106:107], v[192:193], v[106:107]
	v_pk_add_f32 v[112:113], v[186:187], v[112:113]
	v_pk_add_f32 v[108:109], v[190:191], v[108:109]
	v_pk_mul_f32 v[188:189], v[198:199], v[110:111]
	v_pk_mul_f32 v[186:187], v[200:201], v[112:113]
	v_pk_mul_f32 v[190:191], v[202:203], v[106:107]
	v_pk_mul_f32 v[192:193], v[204:205], v[108:109]
	v_cvt_pk_bf16_f32 v186, v186, v187
	v_cvt_pk_bf16_f32 v187, v188, v189
	s_nop 0
	v_cvt_pk_bf16_f32 v188, v192, v193
	v_cvt_pk_bf16_f32 v189, v190, v191
	v_lshl_add_u64 v[190:191], s[96:97], 0, v[194:195]
	global_store_dwordx4 v[190:191], v[186:189], off
	s_nop 1
	v_lshl_add_u64 v[188:189], v[184:185], 0, s[4:5]
	v_lshl_add_u64 v[212:213], v[188:189], 0, v[148:149]
	v_lshl_add_u64 v[186:187], v[212:213], 2, s[44:45]
	global_load_dwordx4 v[190:193], v[186:187], off nt
	global_load_dwordx4 v[194:197], v[186:187], off offset:16 nt
	v_lshlrev_b64 v[212:213], 1, v[212:213]
	v_cvt_pk_bf16_f32 v94, v94, v95
	v_cvt_pk_bf16_f32 v95, v96, v97
	v_cvt_pk_bf16_f32 v96, v90, v91
	v_cvt_pk_bf16_f32 v97, v92, v93
	v_lshl_add_u64 v[90:91], s[90:91], 0, v[212:213]
	global_store_dwordx4 v[90:91], v[94:97], off
	v_lshlrev_b32_e32 v92, 16, v96
	v_and_b32_e32 v93, 0xffff0000, v96
	v_lshlrev_b32_e32 v90, 16, v97
	v_and_b32_e32 v91, 0xffff0000, v97
	v_lshlrev_b32_e32 v96, 16, v94
	v_and_b32_e32 v97, 0xffff0000, v94
	v_lshlrev_b32_e32 v94, 16, v95
	v_and_b32_e32 v95, 0xffff0000, v95
	s_mov_b64 s[4:5], 0x50000
	s_waitcnt vmcnt(2)
	v_pk_add_f32 v[94:95], v[192:193], v[94:95]
	s_waitcnt vmcnt(1)
	v_pk_add_f32 v[90:91], v[196:197], v[90:91]
	v_pk_add_f32 v[96:97], v[190:191], v[96:97]
	v_pk_add_f32 v[92:93], v[194:195], v[92:93]
	v_pk_mul_f32 v[192:193], v[198:199], v[94:95]
	v_pk_mul_f32 v[190:191], v[200:201], v[96:97]
	v_pk_mul_f32 v[194:195], v[202:203], v[90:91]
	v_pk_mul_f32 v[196:197], v[204:205], v[92:93]
	v_cvt_pk_bf16_f32 v190, v190, v191
	v_cvt_pk_bf16_f32 v191, v192, v193
	s_nop 0
	v_cvt_pk_bf16_f32 v192, v196, v197
	v_cvt_pk_bf16_f32 v193, v194, v195
	v_lshl_add_u64 v[194:195], s[96:97], 0, v[212:213]
	global_store_dwordx4 v[194:195], v[190:193], off
	s_nop 1
	v_lshl_add_u64 v[192:193], v[184:185], 0, s[4:5]
	v_lshl_add_u64 v[220:221], v[192:193], 0, v[148:149]
	v_lshl_add_u64 v[190:191], v[220:221], 2, s[44:45]
	global_load_dwordx4 v[194:197], v[190:191], off nt
	global_load_dwordx4 v[212:215], v[190:191], off offset:16 nt
	v_lshlrev_b64 v[220:221], 1, v[220:221]
	v_cvt_pk_bf16_f32 v86, v86, v87
	v_cvt_pk_bf16_f32 v87, v88, v89
	v_cvt_pk_bf16_f32 v88, v82, v83
	v_cvt_pk_bf16_f32 v89, v84, v85
	v_lshl_add_u64 v[82:83], s[90:91], 0, v[220:221]
	global_store_dwordx4 v[82:83], v[86:89], off
	v_lshlrev_b32_e32 v84, 16, v88
	v_and_b32_e32 v85, 0xffff0000, v88
	v_lshlrev_b32_e32 v82, 16, v89
	v_and_b32_e32 v83, 0xffff0000, v89
	v_lshlrev_b32_e32 v88, 16, v86
	v_and_b32_e32 v89, 0xffff0000, v86
	v_lshlrev_b32_e32 v86, 16, v87
	v_and_b32_e32 v87, 0xffff0000, v87
	s_mov_b64 s[4:5], 0x58000
	s_waitcnt vmcnt(2)
; __device__ __forceinline__ unsigned cvt_pk_bf16(float lo, float hi) { unsigned r; asm volatile("v_cvt_pk_bf16_f32 %0, %1, %2" : "=v"(r) : "v"(lo), "v"(hi)); return r; }
;     __device__ __forceinline__ void operator()(const f32x4 (&acc)[2][2][4][2], const Unit& u, int wr, int wc, int fr, int fq) const {
;     ...
;                 for (int m = 0; m < 4; ++m) { const size_t off = (size_t)(row0 + ai * HALF + m * 16) * 2048 + col0 + bj * HALF;
;                     f32x4 x0 = __builtin_nontemporal_load((const f32x4*)(base + off)), x1 = __builtin_nontemporal_load((const f32x4*)(base + off + 4));
;                     if constexpr (HAS_DIN) { const u32x4 dw = __builtin_nontemporal_load((const u32x4*)(dbuf + off));
;                         x0 += (f32x4){__builtin_bit_cast(float, dw.x << 16), __builtin_bit_cast(float, dw.x & 0xffff0000u), __builtin_bit_cast(float, dw.y << 16), __builtin_bit_cast(float, dw.y & 0xffff0000u)};
;                         x1 += (f32x4){__builtin_bit_cast(float, dw.z << 16), __builtin_bit_cast(float, dw.z & 0xffff0000u), __builtin_bit_cast(float, dw.w << 16), __builtin_bit_cast(float, dw.w & 0xffff0000u)}; }
;                     f32x4 o0, o1;
;                     if constexpr (OUT_DELTA) { const f32x4 d0 = g0 * acc[ai][bj][m][0], d1 = g1 * acc[ai][bj][m][1];
;                         u32x4 w; w.x = cvt_pk_bf16(d0[0], d0[1]); w.y = cvt_pk_bf16(d0[2], d0[3]); w.z = cvt_pk_bf16(d1[0], d1[1]); w.w = cvt_pk_bf16(d1[2], d1[3]);
;                         *(u32x4*)(dbuf + off) = w;
;                         o0 = x0 + (f32x4){__builtin_bit_cast(float, w.x << 16), __builtin_bit_cast(float, w.x & 0xffff0000u), __builtin_bit_cast(float, w.y << 16), __builtin_bit_cast(float, w.y & 0xffff0000u)};
;                         o1 = x1 + (f32x4){__builtin_bit_cast(float, w.z << 16), __builtin_bit_cast(float, w.z & 0xffff0000u), __builtin_bit_cast(float, w.w << 16), __builtin_bit_cast(float, w.w & 0xffff0000u)}; }
;                     else { o0 = x0 + g0 * acc[ai][bj][m][0]; o1 = x1 + g1 * acc[ai][bj][m][1]; *(f32x4*)(out + off) = o0; *(f32x4*)(out + off + 4) = o1; }
;                     if (Hn) { const f32x4 h0 = o0 * G0, h1 = o1 * G1;
;                         u32x4 w; w.x = cvt_pk_bf16(h0[0], h0[1]); w.y = cvt_pk_bf16(h0[2], h0[3]); w.z = cvt_pk_bf16(h1[0], h1[1]); w.w = cvt_pk_bf16(h1[2], h1[3]);
;                         *(u32x4*)(Hn + off) = w;
	v_pk_add_f32 v[86:87], v[196:197], v[86:87]
	s_waitcnt vmcnt(1)
	v_pk_add_f32 v[82:83], v[214:215], v[82:83]
	v_pk_add_f32 v[88:89], v[194:195], v[88:89]
	v_pk_add_f32 v[84:85], v[212:213], v[84:85]
	v_pk_mul_f32 v[196:197], v[198:199], v[86:87]
	v_pk_mul_f32 v[194:195], v[200:201], v[88:89]
	v_pk_mul_f32 v[212:213], v[202:203], v[82:83]
	v_pk_mul_f32 v[214:215], v[204:205], v[84:85]
	v_cvt_pk_bf16_f32 v194, v194, v195
	v_cvt_pk_bf16_f32 v195, v196, v197
	s_nop 0
	v_cvt_pk_bf16_f32 v196, v214, v215
	v_cvt_pk_bf16_f32 v197, v212, v213
	v_lshl_add_u64 v[212:213], s[96:97], 0, v[220:221]
	global_store_dwordx4 v[212:213], v[194:197], off
	s_nop 1
	v_lshl_add_u64 v[196:197], v[184:185], 0, s[4:5]
	v_lshl_add_u64 v[224:225], v[196:197], 0, v[148:149]
	v_lshl_add_u64 v[194:195], v[224:225], 2, s[44:45]
	global_load_dwordx4 v[212:215], v[194:195], off nt
	global_load_dwordx4 v[220:223], v[194:195], off offset:16 nt
	v_lshlrev_b64 v[102:103], 1, v[224:225]
	v_cvt_pk_bf16_f32 v78, v78, v79
	v_cvt_pk_bf16_f32 v79, v80, v81
	v_cvt_pk_bf16_f32 v80, v74, v75
	v_cvt_pk_bf16_f32 v81, v76, v77
	v_lshl_add_u64 v[74:75], s[90:91], 0, v[102:103]
	global_store_dwordx4 v[74:75], v[78:81], off
	v_lshlrev_b32_e32 v76, 16, v80
	v_and_b32_e32 v77, 0xffff0000, v80
	v_lshlrev_b32_e32 v74, 16, v81
	v_and_b32_e32 v75, 0xffff0000, v81
	v_lshlrev_b32_e32 v80, 16, v78
	v_and_b32_e32 v81, 0xffff0000, v78
	v_lshlrev_b32_e32 v78, 16, v79
	v_and_b32_e32 v79, 0xffff0000, v79
	v_lshl_add_u64 v[102:103], s[96:97], 0, v[102:103]
	v_or_b32_e32 v148, 0x80, v148
	s_waitcnt vmcnt(2)
	v_pk_add_f32 v[78:79], v[214:215], v[78:79]
	v_pk_add_f32 v[80:81], v[212:213], v[80:81]
	s_waitcnt vmcnt(1)
	v_pk_add_f32 v[74:75], v[222:223], v[74:75]
	v_pk_add_f32 v[76:77], v[220:221], v[76:77]
	v_pk_mul_f32 v[100:101], v[198:199], v[78:79]
	v_pk_mul_f32 v[98:99], v[200:201], v[80:81]
	v_pk_mul_f32 v[104:105], v[202:203], v[74:75]
	v_pk_mul_f32 v[198:199], v[204:205], v[76:77]
	v_cvt_pk_bf16_f32 v98, v98, v99
	v_cvt_pk_bf16_f32 v99, v100, v101
	s_nop 0
	v_cvt_pk_bf16_f32 v100, v198, v199
	v_cvt_pk_bf16_f32 v101, v104, v105
	global_store_dwordx4 v[102:103], v[98:101], off
	global_load_dwordx4 v[100:103], v[178:179], off offset:512 nt
	global_load_dwordx4 v[198:201], v[178:179], off offset:528 nt
	v_lshl_add_u64 v[98:99], v[184:185], 0, v[148:149]
	v_pk_mul_f32 v[104:105], v[68:69], v[28:29]
	v_pk_mul_f32 v[68:69], v[66:67], v[26:27]
	v_cvt_pk_bf16_f32 v66, v70, v71
	v_cvt_pk_bf16_f32 v67, v72, v73
	s_nop 0
	v_cvt_pk_bf16_f32 v68, v68, v69
	v_cvt_pk_bf16_f32 v69, v104, v105
	v_lshlrev_b64 v[104:105], 1, v[98:99]
	v_lshl_add_u64 v[70:71], s[90:91], 0, v[104:105]
	global_store_dwordx4 v[70:71], v[66:69], off
	v_lshlrev_b32_e32 v72, 16, v68
	v_and_b32_e32 v73, 0xffff0000, v68
	v_lshlrev_b32_e32 v68, 16, v69
	v_and_b32_e32 v69, 0xffff0000, v69
	s_waitcnt vmcnt(1)
	v_pk_add_f32 v[70:71], v[200:201], v[68:69]
	v_lshlrev_b32_e32 v68, 16, v66
	v_and_b32_e32 v69, 0xffff0000, v66
	v_lshlrev_b32_e32 v66, 16, v67
	v_and_b32_e32 v67, 0xffff0000, v67
	v_pk_add_f32 v[98:99], v[102:103], v[66:67]
	v_pk_add_f32 v[100:101], v[100:101], v[68:69]
	v_pk_add_f32 v[72:73], v[198:199], v[72:73]
	v_pk_mul_f32 v[68:69], v[150:151], v[98:99]
	v_pk_mul_f32 v[66:67], v[152:153], v[100:101]
	v_pk_mul_f32 v[102:103], v[154:155], v[70:71]
	v_pk_mul_f32 v[178:179], v[156:157], v[72:73]
	v_cvt_pk_bf16_f32 v66, v66, v67
	v_cvt_pk_bf16_f32 v67, v68, v69
	s_nop 0
	v_cvt_pk_bf16_f32 v68, v178, v179
	v_cvt_pk_bf16_f32 v69, v102, v103
	v_lshl_add_u64 v[102:103], s[96:97], 0, v[104:105]
	global_store_dwordx4 v[102:103], v[66:69], off
	s_nop 1
	v_mul_f32_e32 v66, v101, v101
	v_mul_f32_e32 v67, v99, v99
	v_fmac_f32_e32 v66, v100, v100
	v_fmac_f32_e32 v67, v98, v98
	v_add_f32_e32 v66, v66, v67
	v_mul_f32_e32 v67, v73, v73
	v_mul_f32_e32 v68, v71, v71
	v_fmac_f32_e32 v67, v72, v72
	v_fmac_f32_e32 v68, v70, v70
	v_add_f32_e32 v67, v67, v68
	global_load_dwordx4 v[68:71], v[138:139], off offset:512 nt
	global_load_dwordx4 v[98:101], v[138:139], off offset:528 nt
	v_lshl_add_u64 v[72:73], v[140:141], 0, v[148:149]
	v_lshlrev_b64 v[72:73], 1, v[72:73]
	v_cvt_pk_bf16_f32 v62, v62, v63
	v_cvt_pk_bf16_f32 v63, v64, v65
	v_cvt_pk_bf16_f32 v64, v58, v59
	v_cvt_pk_bf16_f32 v65, v60, v61
	v_lshl_add_u64 v[58:59], s[90:91], 0, v[72:73]
	global_store_dwordx4 v[58:59], v[62:65], off
	v_lshlrev_b32_e32 v60, 16, v64
	v_and_b32_e32 v61, 0xffff0000, v64
	v_lshlrev_b32_e32 v58, 16, v65
	v_and_b32_e32 v59, 0xffff0000, v65
	v_lshlrev_b32_e32 v64, 16, v62
	v_and_b32_e32 v65, 0xffff0000, v62
	v_lshlrev_b32_e32 v62, 16, v63
	v_and_b32_e32 v63, 0xffff0000, v63
	v_lshl_add_u64 v[72:73], s[96:97], 0, v[72:73]
	v_add_f32_e32 v66, v66, v67
	v_add_f32_e32 v66, v211, v66
	s_waitcnt vmcnt(2)
	v_pk_add_f32 v[62:63], v[70:71], v[62:63]
	v_pk_add_f32 v[64:65], v[68:69], v[64:65]
	s_waitcnt vmcnt(1)
	v_pk_add_f32 v[58:59], v[100:101], v[58:59]
	v_pk_add_f32 v[60:61], v[98:99], v[60:61]
	v_pk_mul_f32 v[70:71], v[150:151], v[62:63]
	v_pk_mul_f32 v[68:69], v[152:153], v[64:65]
	v_pk_mul_f32 v[98:99], v[154:155], v[58:59]
	v_pk_mul_f32 v[100:101], v[156:157], v[60:61]
	v_cvt_pk_bf16_f32 v68, v68, v69
	v_cvt_pk_bf16_f32 v69, v70, v71
	s_nop 0
	v_cvt_pk_bf16_f32 v70, v100, v101
	v_cvt_pk_bf16_f32 v71, v98, v99
	global_store_dwordx4 v[72:73], v[68:71], off
	global_load_dwordx4 v[68:71], v[142:143], off offset:512 nt
	s_nop 0
	global_load_dwordx4 v[98:101], v[142:143], off offset:528 nt
	v_lshl_add_u64 v[72:73], v[144:145], 0, v[148:149]
	v_lshlrev_b64 v[72:73], 1, v[72:73]
	v_cvt_pk_bf16_f32 v54, v54, v55
	v_cvt_pk_bf16_f32 v55, v56, v57
	v_cvt_pk_bf16_f32 v56, v50, v51
	v_cvt_pk_bf16_f32 v57, v52, v53
	v_lshl_add_u64 v[50:51], s[90:91], 0, v[72:73]
	global_store_dwordx4 v[50:51], v[54:57], off
	v_lshlrev_b32_e32 v52, 16, v56
	v_and_b32_e32 v53, 0xffff0000, v56
	v_lshlrev_b32_e32 v50, 16, v57
	v_and_b32_e32 v51, 0xffff0000, v57
	v_lshlrev_b32_e32 v56, 16, v54
	v_and_b32_e32 v57, 0xffff0000, v54
	v_lshlrev_b32_e32 v54, 16, v55
	v_and_b32_e32 v55, 0xffff0000, v55
	v_lshl_add_u64 v[72:73], s[96:97], 0, v[72:73]
	s_waitcnt vmcnt(2)
; __device__ __forceinline__ unsigned cvt_pk_bf16(float lo, float hi) { unsigned r; asm volatile("v_cvt_pk_bf16_f32 %0, %1, %2" : "=v"(r) : "v"(lo), "v"(hi)); return r; }
;     __device__ __forceinline__ void operator()(const f32x4 (&acc)[2][2][4][2], const Unit& u, int wr, int wc, int fr, int fq) const {
;     ...
;                 for (int m = 0; m < 4; ++m) { const size_t off = (size_t)(row0 + ai * HALF + m * 16) * 2048 + col0 + bj * HALF;
;                     f32x4 x0 = __builtin_nontemporal_load((const f32x4*)(base + off)), x1 = __builtin_nontemporal_load((const f32x4*)(base + off + 4));
;                     if constexpr (HAS_DIN) { const u32x4 dw = __builtin_nontemporal_load((const u32x4*)(dbuf + off));
;                         x0 += (f32x4){__builtin_bit_cast(float, dw.x << 16), __builtin_bit_cast(float, dw.x & 0xffff0000u), __builtin_bit_cast(float, dw.y << 16), __builtin_bit_cast(float, dw.y & 0xffff0000u)};
;                         x1 += (f32x4){__builtin_bit_cast(float, dw.z << 16), __builtin_bit_cast(float, dw.z & 0xffff0000u), __builtin_bit_cast(float, dw.w << 16), __builtin_bit_cast(float, dw.w & 0xffff0000u)}; }
;                     f32x4 o0, o1;
;                     if constexpr (OUT_DELTA) { const f32x4 d0 = g0 * acc[ai][bj][m][0], d1 = g1 * acc[ai][bj][m][1];
;                         u32x4 w; w.x = cvt_pk_bf16(d0[0], d0[1]); w.y = cvt_pk_bf16(d0[2], d0[3]); w.z = cvt_pk_bf16(d1[0], d1[1]); w.w = cvt_pk_bf16(d1[2], d1[3]);
;                         *(u32x4*)(dbuf + off) = w;
;                         o0 = x0 + (f32x4){__builtin_bit_cast(float, w.x << 16), __builtin_bit_cast(float, w.x & 0xffff0000u), __builtin_bit_cast(float, w.y << 16), __builtin_bit_cast(float, w.y & 0xffff0000u)};
;                         o1 = x1 + (f32x4){__builtin_bit_cast(float, w.z << 16), __builtin_bit_cast(float, w.z & 0xffff0000u), __builtin_bit_cast(float, w.w << 16), __builtin_bit_cast(float, w.w & 0xffff0000u)}; }
;                     else { o0 = x0 + g0 * acc[ai][bj][m][0]; o1 = x1 + g1 * acc[ai][bj][m][1]; *(f32x4*)(out + off) = o0; *(f32x4*)(out + off + 4) = o1; }
;                     if (Hn) { const f32x4 h0 = o0 * G0, h1 = o1 * G1;
;                         u32x4 w; w.x = cvt_pk_bf16(h0[0], h0[1]); w.y = cvt_pk_bf16(h0[2], h0[3]); w.z = cvt_pk_bf16(h1[0], h1[1]); w.w = cvt_pk_bf16(h1[2], h1[3]);
;                         *(u32x4*)(Hn + off) = w;
	v_pk_add_f32 v[54:55], v[70:71], v[54:55]
	v_pk_add_f32 v[56:57], v[68:69], v[56:57]
	s_waitcnt vmcnt(1)
	v_pk_add_f32 v[50:51], v[100:101], v[50:51]
	v_pk_add_f32 v[52:53], v[98:99], v[52:53]
	v_pk_mul_f32 v[70:71], v[150:151], v[54:55]
	v_pk_mul_f32 v[68:69], v[152:153], v[56:57]
	v_pk_mul_f32 v[98:99], v[154:155], v[50:51]
	v_pk_mul_f32 v[100:101], v[156:157], v[52:53]
	v_cvt_pk_bf16_f32 v68, v68, v69
	v_cvt_pk_bf16_f32 v69, v70, v71
	s_nop 0
	v_cvt_pk_bf16_f32 v70, v100, v101
	v_cvt_pk_bf16_f32 v71, v98, v99
	global_store_dwordx4 v[72:73], v[68:71], off
	global_load_dwordx4 v[68:71], v[158:159], off offset:512 nt
	s_nop 0
	global_load_dwordx4 v[98:101], v[158:159], off offset:528 nt
	v_lshl_add_u64 v[72:73], v[160:161], 0, v[148:149]
	v_lshlrev_b64 v[72:73], 1, v[72:73]
	v_cvt_pk_bf16_f32 v46, v46, v47
	v_cvt_pk_bf16_f32 v47, v48, v49
	v_cvt_pk_bf16_f32 v48, v42, v43
	v_cvt_pk_bf16_f32 v49, v44, v45
	v_lshl_add_u64 v[42:43], s[90:91], 0, v[72:73]
	global_store_dwordx4 v[42:43], v[46:49], off
	v_lshlrev_b32_e32 v44, 16, v48
	v_and_b32_e32 v45, 0xffff0000, v48
	v_lshlrev_b32_e32 v42, 16, v49
	v_and_b32_e32 v43, 0xffff0000, v49
	v_lshlrev_b32_e32 v48, 16, v46
	v_and_b32_e32 v49, 0xffff0000, v46
	v_lshlrev_b32_e32 v46, 16, v47
	v_and_b32_e32 v47, 0xffff0000, v47
	v_lshl_add_u64 v[72:73], s[96:97], 0, v[72:73]
	s_waitcnt vmcnt(2)
	v_pk_add_f32 v[46:47], v[70:71], v[46:47]
	v_pk_add_f32 v[48:49], v[68:69], v[48:49]
	s_waitcnt vmcnt(1)
	v_pk_add_f32 v[42:43], v[100:101], v[42:43]
	v_pk_add_f32 v[44:45], v[98:99], v[44:45]
	v_pk_mul_f32 v[70:71], v[150:151], v[46:47]
	v_pk_mul_f32 v[68:69], v[152:153], v[48:49]
	v_pk_mul_f32 v[98:99], v[154:155], v[42:43]
	v_pk_mul_f32 v[100:101], v[156:157], v[44:45]
	v_cvt_pk_bf16_f32 v68, v68, v69
	v_cvt_pk_bf16_f32 v69, v70, v71
	s_nop 0
	v_cvt_pk_bf16_f32 v70, v100, v101
	v_cvt_pk_bf16_f32 v71, v98, v99
	global_store_dwordx4 v[72:73], v[68:71], off
	global_load_dwordx4 v[68:71], v[180:181], off offset:512 nt
	s_nop 0
	global_load_dwordx4 v[98:101], v[180:181], off offset:528 nt
	v_lshl_add_u64 v[72:73], v[182:183], 0, v[148:149]
	v_lshlrev_b64 v[72:73], 1, v[72:73]
	v_cvt_pk_bf16_f32 v38, v38, v39
	v_cvt_pk_bf16_f32 v39, v40, v41
	v_cvt_pk_bf16_f32 v40, v34, v35
	v_cvt_pk_bf16_f32 v41, v36, v37
	v_lshl_add_u64 v[34:35], s[90:91], 0, v[72:73]
	global_store_dwordx4 v[34:35], v[38:41], off
	v_lshlrev_b32_e32 v36, 16, v40
	v_and_b32_e32 v37, 0xffff0000, v40
	v_lshlrev_b32_e32 v34, 16, v41
	v_and_b32_e32 v35, 0xffff0000, v41
	v_lshlrev_b32_e32 v40, 16, v38
	v_and_b32_e32 v41, 0xffff0000, v38
	v_lshlrev_b32_e32 v38, 16, v39
	v_and_b32_e32 v39, 0xffff0000, v39
	v_lshl_add_u64 v[72:73], s[96:97], 0, v[72:73]
	s_waitcnt vmcnt(2)
	v_pk_add_f32 v[38:39], v[70:71], v[38:39]
	v_pk_add_f32 v[40:41], v[68:69], v[40:41]
	s_waitcnt vmcnt(1)
	v_pk_add_f32 v[34:35], v[100:101], v[34:35]
	v_pk_add_f32 v[36:37], v[98:99], v[36:37]
	v_pk_mul_f32 v[70:71], v[150:151], v[38:39]
	v_pk_mul_f32 v[68:69], v[152:153], v[40:41]
	v_pk_mul_f32 v[98:99], v[154:155], v[34:35]
	v_pk_mul_f32 v[100:101], v[156:157], v[36:37]
	v_cvt_pk_bf16_f32 v68, v68, v69
	v_cvt_pk_bf16_f32 v69, v70, v71
	s_nop 0
	v_cvt_pk_bf16_f32 v70, v100, v101
	v_cvt_pk_bf16_f32 v71, v98, v99
	global_store_dwordx4 v[72:73], v[68:71], off
	global_load_dwordx4 v[68:71], v[186:187], off offset:512 nt
	s_nop 0
	global_load_dwordx4 v[98:101], v[186:187], off offset:528 nt
	v_lshl_add_u64 v[72:73], v[188:189], 0, v[148:149]
	v_lshlrev_b64 v[72:73], 1, v[72:73]
	v_cvt_pk_bf16_f32 v22, v22, v23
	v_cvt_pk_bf16_f32 v23, v24, v25
	v_cvt_pk_bf16_f32 v24, v18, v19
	v_cvt_pk_bf16_f32 v25, v20, v21
	v_lshl_add_u64 v[18:19], s[90:91], 0, v[72:73]
	global_store_dwordx4 v[18:19], v[22:25], off
	v_lshlrev_b32_e32 v20, 16, v24
	v_and_b32_e32 v21, 0xffff0000, v24
	v_lshlrev_b32_e32 v18, 16, v25
	v_and_b32_e32 v19, 0xffff0000, v25
	v_lshlrev_b32_e32 v24, 16, v22
	v_and_b32_e32 v25, 0xffff0000, v22
	v_lshlrev_b32_e32 v22, 16, v23
	v_and_b32_e32 v23, 0xffff0000, v23
	v_lshl_add_u64 v[72:73], s[96:97], 0, v[72:73]
	s_waitcnt vmcnt(2)
	v_pk_add_f32 v[22:23], v[70:71], v[22:23]
	v_pk_add_f32 v[24:25], v[68:69], v[24:25]
	s_waitcnt vmcnt(1)
; __device__ __forceinline__ unsigned cvt_pk_bf16(float lo, float hi) { unsigned r; asm volatile("v_cvt_pk_bf16_f32 %0, %1, %2" : "=v"(r) : "v"(lo), "v"(hi)); return r; }
;     __device__ __forceinline__ void operator()(const f32x4 (&acc)[2][2][4][2], const Unit& u, int wr, int wc, int fr, int fq) const {
;     ...
;                 for (int m = 0; m < 4; ++m) { const size_t off = (size_t)(row0 + ai * HALF + m * 16) * 2048 + col0 + bj * HALF;
;                     f32x4 x0 = __builtin_nontemporal_load((const f32x4*)(base + off)), x1 = __builtin_nontemporal_load((const f32x4*)(base + off + 4));
;                     if constexpr (HAS_DIN) { const u32x4 dw = __builtin_nontemporal_load((const u32x4*)(dbuf + off));
;                         x0 += (f32x4){__builtin_bit_cast(float, dw.x << 16), __builtin_bit_cast(float, dw.x & 0xffff0000u), __builtin_bit_cast(float, dw.y << 16), __builtin_bit_cast(float, dw.y & 0xffff0000u)};
;                         x1 += (f32x4){__builtin_bit_cast(float, dw.z << 16), __builtin_bit_cast(float, dw.z & 0xffff0000u), __builtin_bit_cast(float, dw.w << 16), __builtin_bit_cast(float, dw.w & 0xffff0000u)}; }
;                     f32x4 o0, o1;
;                     if constexpr (OUT_DELTA) { const f32x4 d0 = g0 * acc[ai][bj][m][0], d1 = g1 * acc[ai][bj][m][1];
;                         u32x4 w; w.x = cvt_pk_bf16(d0[0], d0[1]); w.y = cvt_pk_bf16(d0[2], d0[3]); w.z = cvt_pk_bf16(d1[0], d1[1]); w.w = cvt_pk_bf16(d1[2], d1[3]);
;                         *(u32x4*)(dbuf + off) = w;
;                         o0 = x0 + (f32x4){__builtin_bit_cast(float, w.x << 16), __builtin_bit_cast(float, w.x & 0xffff0000u), __builtin_bit_cast(float, w.y << 16), __builtin_bit_cast(float, w.y & 0xffff0000u)};
;                         o1 = x1 + (f32x4){__builtin_bit_cast(float, w.z << 16), __builtin_bit_cast(float, w.z & 0xffff0000u), __builtin_bit_cast(float, w.w << 16), __builtin_bit_cast(float, w.w & 0xffff0000u)}; }
;                     else { o0 = x0 + g0 * acc[ai][bj][m][0]; o1 = x1 + g1 * acc[ai][bj][m][1]; *(f32x4*)(out + off) = o0; *(f32x4*)(out + off + 4) = o1; }
;                     if (Hn) { const f32x4 h0 = o0 * G0, h1 = o1 * G1;
;                         u32x4 w; w.x = cvt_pk_bf16(h0[0], h0[1]); w.y = cvt_pk_bf16(h0[2], h0[3]); w.z = cvt_pk_bf16(h1[0], h1[1]); w.w = cvt_pk_bf16(h1[2], h1[3]);
;                         *(u32x4*)(Hn + off) = w;
	v_pk_add_f32 v[18:19], v[100:101], v[18:19]
	v_pk_add_f32 v[20:21], v[98:99], v[20:21]
	v_pk_mul_f32 v[70:71], v[150:151], v[22:23]
	v_pk_mul_f32 v[68:69], v[152:153], v[24:25]
	v_pk_mul_f32 v[98:99], v[154:155], v[18:19]
	v_pk_mul_f32 v[100:101], v[156:157], v[20:21]
	v_cvt_pk_bf16_f32 v68, v68, v69
	v_cvt_pk_bf16_f32 v69, v70, v71
	s_nop 0
	v_cvt_pk_bf16_f32 v70, v100, v101
	v_cvt_pk_bf16_f32 v71, v98, v99
	global_store_dwordx4 v[72:73], v[68:71], off
	global_load_dwordx4 v[68:71], v[190:191], off offset:512 nt
	s_nop 0
	global_load_dwordx4 v[98:101], v[190:191], off offset:528 nt
	v_lshl_add_u64 v[72:73], v[192:193], 0, v[148:149]
	v_lshlrev_b64 v[72:73], 1, v[72:73]
	v_cvt_pk_bf16_f32 v14, v14, v15
	v_cvt_pk_bf16_f32 v15, v16, v17
	v_cvt_pk_bf16_f32 v16, v10, v11
	v_cvt_pk_bf16_f32 v17, v12, v13
	v_lshl_add_u64 v[10:11], s[90:91], 0, v[72:73]
	global_store_dwordx4 v[10:11], v[14:17], off
	v_lshlrev_b32_e32 v12, 16, v16
	v_and_b32_e32 v13, 0xffff0000, v16
	v_lshlrev_b32_e32 v10, 16, v17
	v_and_b32_e32 v11, 0xffff0000, v17
	v_lshlrev_b32_e32 v16, 16, v14
	v_and_b32_e32 v17, 0xffff0000, v14
	v_lshlrev_b32_e32 v14, 16, v15
	v_and_b32_e32 v15, 0xffff0000, v15
	v_lshl_add_u64 v[72:73], s[96:97], 0, v[72:73]
	s_waitcnt vmcnt(2)
	v_pk_add_f32 v[14:15], v[70:71], v[14:15]
	v_pk_add_f32 v[16:17], v[68:69], v[16:17]
	s_waitcnt vmcnt(1)
	v_pk_add_f32 v[10:11], v[100:101], v[10:11]
	v_pk_add_f32 v[12:13], v[98:99], v[12:13]
	v_pk_mul_f32 v[70:71], v[150:151], v[14:15]
	v_pk_mul_f32 v[68:69], v[152:153], v[16:17]
	v_pk_mul_f32 v[98:99], v[154:155], v[10:11]
	v_pk_mul_f32 v[100:101], v[156:157], v[12:13]
	v_cvt_pk_bf16_f32 v68, v68, v69
	v_cvt_pk_bf16_f32 v69, v70, v71
	s_nop 0
	v_cvt_pk_bf16_f32 v70, v100, v101
	v_cvt_pk_bf16_f32 v71, v98, v99
	global_store_dwordx4 v[72:73], v[68:71], off
	global_load_dwordx4 v[68:71], v[194:195], off offset:512 nt
	s_nop 0
	global_load_dwordx4 v[98:101], v[194:195], off offset:528 nt
	v_lshl_add_u64 v[72:73], v[196:197], 0, v[148:149]
	v_lshlrev_b64 v[30:31], 1, v[72:73]
	v_cvt_pk_bf16_f32 v6, v6, v7
	v_cvt_pk_bf16_f32 v7, v8, v9
	v_cvt_pk_bf16_f32 v8, v2, v3
	v_cvt_pk_bf16_f32 v9, v4, v5
	v_lshl_add_u64 v[2:3], s[90:91], 0, v[30:31]
	global_store_dwordx4 v[2:3], v[6:9], off
	v_lshlrev_b32_e32 v4, 16, v8
	v_and_b32_e32 v5, 0xffff0000, v8
	v_lshlrev_b32_e32 v2, 16, v9
	v_and_b32_e32 v3, 0xffff0000, v9
	v_lshlrev_b32_e32 v8, 16, v6
	v_and_b32_e32 v9, 0xffff0000, v6
	v_lshlrev_b32_e32 v6, 16, v7
	v_and_b32_e32 v7, 0xffff0000, v7
	v_lshl_add_u64 v[30:31], s[96:97], 0, v[30:31]
	s_waitcnt vmcnt(2)
	v_pk_add_f32 v[8:9], v[68:69], v[8:9]
	v_pk_add_f32 v[6:7], v[70:71], v[6:7]
	v_pk_mul_f32 v[26:27], v[152:153], v[8:9]
	s_waitcnt vmcnt(1)
	v_pk_add_f32 v[2:3], v[100:101], v[2:3]
	v_pk_add_f32 v[4:5], v[98:99], v[4:5]
	v_pk_mul_f32 v[28:29], v[150:151], v[6:7]
	v_cvt_pk_bf16_f32 v26, v26, v27
	v_pk_mul_f32 v[32:33], v[154:155], v[2:3]
	v_cvt_pk_bf16_f32 v27, v28, v29
	v_pk_mul_f32 v[68:69], v[156:157], v[4:5]
	s_nop 0
	v_cvt_pk_bf16_f32 v28, v68, v69
	v_cvt_pk_bf16_f32 v29, v32, v33
	global_store_dwordx4 v[30:31], v[26:29], off
	s_nop 1
	v_and_b32_e32 v27, 64, v218
	v_xor_b32_e32 v26, 16, v218
	v_add_u32_e32 v27, 64, v27
	v_cmp_lt_i32_e32 vcc, v26, v27
	s_nop 1
	v_cndmask_b32_e32 v26, v218, v26, vcc
	v_lshlrev_b32_e32 v28, 2, v26
	v_xor_b32_e32 v26, 32, v218
	v_cmp_lt_i32_e32 vcc, v26, v27
	s_nop 1
	v_cndmask_b32_e32 v26, v218, v26, vcc
	v_lshlrev_b32_e32 v29, 2, v26
	ds_bpermute_b32 v26, v28, v66
	s_waitcnt lgkmcnt(0)
	v_add_f32_e32 v30, v66, v26
	ds_bpermute_b32 v31, v29, v30
	v_lshl_add_u64 v[26:27], v[146:147], 3, s[42:43]
	s_and_saveexec_b64 s[4:5], s[0:1]
	s_mov_b32 s8, 0x2f800000
	s_mov_b32 s9, 0xcf800000
	s_cbranch_execz .LBB0_558
	s_waitcnt lgkmcnt(0)
	v_add_f32_e32 v30, v30, v31
	v_mul_f32_e32 v30, 0x47800000, v30
	v_rndne_f32_e32 v30, v30
	v_mul_f32_e64 v31, |v30|, s8
	v_floor_f32_e32 v31, v31
	v_fma_f32 v32, v31, s9, |v30|
	v_cvt_u32_f32_e32 v32, v32
	v_cvt_u32_f32_e32 v31, v31
	v_ashrrev_i32_e32 v33, 31, v30
	v_xor_b32_e32 v30, v32, v33
	v_xor_b32_e32 v31, v31, v33
	v_sub_co_u32_e32 v30, vcc, v30, v33
	s_nop 1
	v_subb_co_u32_e32 v31, vcc, v31, v33, vcc
	global_atomic_add_x2 v[26:27], v[30:31], off

; #define PG8_STAGE(bufoff, gbase, voff) do { const char* gb_ = (const char*)(gbase); asm volatile("" : "+s"(gb_)); _Pragma("unroll") for (int _i = 0; _i < 2; ++_i) { unsigned vo_ = (voff)[_i]; asm volatile("" : "+v"(vo_));        \
;         __builtin_amdgcn_global_load_lds((const unsigned*)(gb_ + vo_), (PG8_LAS unsigned*)(lds + (bufoff) + ldsw + _i * 8192), 16, 0, 0); } } while (0)
; #define PG8_LDA(dst, b, h) do { _Pragma("unroll") for (int m = 0; m < 4; ++m) _Pragma("unroll") for (int k = 0; k < 2; ++k) dst[m][k] = *(const PG8_LAS bf16x8*)(lds + PG8_SA(b, h) + aoff + m * 2048 + k * 1024); } while (0)
; #define PG8_LDB(dst, b, h) do { _Pragma("unroll") for (int n = 0; n < 2; ++n) _Pragma("unroll") for (int k = 0; k < 2; ++k) dst[n][k] = *(const PG8_LAS bf16x8*)(lds + PG8_SB(b, h) + boff + n * 2048 + k * 1024); } while (0)
; #define PG8_WAIT_V(n) asm volatile("s_waitcnt vmcnt(" #n ")" ::: "memory")
; #define PG8_WAIT_L(n) asm volatile("s_waitcnt lgkmcnt(" #n ")" ::: "memory")
; #define PG8_BAR __builtin_amdgcn_s_barrier()
; #define PG8_SCHED __builtin_amdgcn_sched_barrier(0)
; template <class Epi, class Sched, bool ALIGN_EPI = false, bool SP2 = false>
; __device__ __forceinline__ void gemm_phase(PG8_LAS unsigned char* lds, const Gemm g, const Sched& S, const Epi& E) {
;     ...
;             if constexpr (SP2) {
;             PG8_LDB(B0, 0, 0); PG8_LDB(B1, 0, 1); PG8_SCHED; PG8_LDA(At, 0, 0); PG8_STAGE(PG8_SA(1, 1), a1 + hstep, voffA);
;             PG8_WAIT_V(8); PG8_WAIT_L(0); PG8_BAR; PG8_MMA(0, 0, At, B0); PG8_MMA(0, 1, At, B1); PG8_BAR; PG8_SCHED;
;             PG8_LDA(At, 0, 1); PG8_STAGE(PG8_SB(0, 0), b2, voffB); PG8_STAGE(PG8_SB(0, 1), b2 + hstep, voffB); PG8_STAGE(PG8_SA(0, 0), a2, voffA);
;             PG8_WAIT_V(8); PG8_WAIT_L(0); PG8_BAR; PG8_MMA(1, 0, At, B0); PG8_MMA(1, 1, At, B1); PG8_BAR; PG8_SCHED;
;             PG8_LDB(B0, 1, 0); PG8_LDB(B1, 1, 1); PG8_SCHED; PG8_LDA(At, 1, 0); PG8_STAGE(PG8_SA(0, 1), a2 + hstep, voffA);
;             PG8_WAIT_V(8); PG8_WAIT_L(0); PG8_BAR; PG8_MMA(0, 0, At, B0); PG8_MMA(0, 1, At, B1); PG8_BAR; PG8_SCHED;
;             PG8_LDA(At, 1, 1); PG8_STAGE(PG8_SB(1, 0), b3, voffB); PG8_STAGE(PG8_SB(1, 1), b3 + hstep, voffB); PG8_STAGE(PG8_SA(1, 0), a3, voffA);
;             PG8_WAIT_V(8); PG8_WAIT_L(0); PG8_BAR; PG8_MMA(1, 0, At, B0); PG8_MMA(1, 1, At, B1); PG8_BAR; PG8_SCHED;
.LBB0_634:
	s_add_u32 s16, s14, 0x100
	s_addc_u32 s17, s15, 0
	s_cmp_eq_u32 s53, 28
	s_cselect_b32 s22, s49, s16
	s_cselect_b32 s23, s7, s17
	s_cselect_b32 s20, s50, s51
	s_cselect_b32 s21, s5, s52
	s_add_u32 s18, s22, 0x80
	s_addc_u32 s19, s23, 0
	s_add_i32 s54, 0, 0x10000
	s_add_i32 s55, 0, 0x14000
	ds_read_b128 v[82:85], v244
	ds_read_b128 v[86:89], v244 offset:1024
	ds_read_b128 v[90:93], v244 offset:2048
	ds_read_b128 v[94:97], v244 offset:3072
	ds_read_b128 v[146:149], v244 offset:16384
	ds_read_b128 v[150:153], v244 offset:17408
	ds_read_b128 v[154:157], v244 offset:18432
	ds_read_b128 v[158:161], v244 offset:19456
	s_add_u32 s14, s14, 0x80080
	s_addc_u32 s15, s15, 0
	ds_read_b128 v[248:251], v188
	ds_read_b128 v[252:255], v188 offset:1024
	ds_read_b128 v[194:197], v188 offset:2048
	ds_read_b128 v[198:201], v188 offset:3072
	ds_read_b128 v[202:205], v188 offset:4096
	ds_read_b128 v[206:209], v188 offset:5120
	ds_read_b128 v[210:213], v188 offset:6144
	ds_read_b128 v[220:223], v188 offset:7168
	s_add_i32 m0, s27, 0xc000
	s_nop 0
	global_load_lds_dwordx4 v1, s[14:15]
	s_add_i32 m0, s27, 0xe000
	s_nop 0
	global_load_lds_dwordx4 v164, s[14:15]
	s_waitcnt vmcnt(8)
	s_waitcnt lgkmcnt(0)
	s_barrier
	s_setprio 1
	s_waitcnt lgkmcnt(0)
	v_mfma_f32_16x16x32_bf16 v[142:145], v[82:85], v[248:251], v[142:145]
	v_mfma_f32_16x16x32_bf16 v[142:145], v[86:89], v[252:255], v[142:145]
	v_mfma_f32_16x16x32_bf16 v[126:129], v[82:85], v[194:197], v[126:129]
	v_mfma_f32_16x16x32_bf16 v[126:129], v[86:89], v[198:201], v[126:129]
	v_mfma_f32_16x16x32_bf16 v[110:113], v[82:85], v[202:205], v[110:113]
	v_mfma_f32_16x16x32_bf16 v[110:113], v[86:89], v[206:209], v[110:113]
	v_mfma_f32_16x16x32_bf16 v[78:81], v[82:85], v[210:213], v[78:81]
	v_mfma_f32_16x16x32_bf16 v[78:81], v[86:89], v[220:223], v[78:81]
	v_mfma_f32_16x16x32_bf16 v[138:141], v[90:93], v[248:251], v[138:141]
	v_mfma_f32_16x16x32_bf16 v[138:141], v[94:97], v[252:255], v[138:141]
	v_mfma_f32_16x16x32_bf16 v[122:125], v[90:93], v[194:197], v[122:125]
	v_mfma_f32_16x16x32_bf16 v[122:125], v[94:97], v[198:201], v[122:125]
	v_mfma_f32_16x16x32_bf16 v[106:109], v[90:93], v[202:205], v[106:109]
	v_mfma_f32_16x16x32_bf16 v[106:109], v[94:97], v[206:209], v[106:109]
	v_mfma_f32_16x16x32_bf16 v[74:77], v[90:93], v[210:213], v[74:77]
	v_mfma_f32_16x16x32_bf16 v[74:77], v[94:97], v[220:223], v[74:77]
	s_setprio 0
	s_setprio 1
	v_mfma_f32_16x16x32_bf16 v[134:137], v[146:149], v[248:251], v[134:137]
	v_mfma_f32_16x16x32_bf16 v[134:137], v[150:153], v[252:255], v[134:137]
	v_mfma_f32_16x16x32_bf16 v[118:121], v[146:149], v[194:197], v[118:121]
	v_mfma_f32_16x16x32_bf16 v[118:121], v[150:153], v[198:201], v[118:121]
	v_mfma_f32_16x16x32_bf16 v[102:105], v[146:149], v[202:205], v[102:105]
	v_mfma_f32_16x16x32_bf16 v[102:105], v[150:153], v[206:209], v[102:105]
	v_mfma_f32_16x16x32_bf16 v[70:73], v[146:149], v[210:213], v[70:73]
	v_mfma_f32_16x16x32_bf16 v[70:73], v[150:153], v[220:223], v[70:73]
	v_mfma_f32_16x16x32_bf16 v[130:133], v[154:157], v[248:251], v[130:133]
	v_mfma_f32_16x16x32_bf16 v[130:133], v[158:161], v[252:255], v[130:133]
	v_mfma_f32_16x16x32_bf16 v[114:117], v[154:157], v[194:197], v[114:117]
	v_mfma_f32_16x16x32_bf16 v[114:117], v[158:161], v[198:201], v[114:117]
	v_mfma_f32_16x16x32_bf16 v[98:101], v[154:157], v[202:205], v[98:101]
	v_mfma_f32_16x16x32_bf16 v[98:101], v[158:161], v[206:209], v[98:101]
	v_mfma_f32_16x16x32_bf16 v[66:69], v[154:157], v[210:213], v[66:69]
	v_mfma_f32_16x16x32_bf16 v[66:69], v[158:161], v[220:223], v[66:69]
	s_setprio 0
	s_barrier
	s_mov_b64 s[14:15], s[20:21]
	s_add_i32 s54, s54, s26
	ds_read_b128 v[248:251], v188 offset:16384
	ds_read_b128 v[252:255], v188 offset:17408
	ds_read_b128 v[194:197], v188 offset:18432
	ds_read_b128 v[198:201], v188 offset:19456
	ds_read_b128 v[202:205], v188 offset:20480
	ds_read_b128 v[206:209], v188 offset:21504
	ds_read_b128 v[210:213], v188 offset:22528
	ds_read_b128 v[220:223], v188 offset:23552
	s_mov_b32 m0, s54
	s_nop 0
	global_load_lds_dwordx4 v162, s[14:15]
	s_add_i32 m0, s54, 0x2000
	s_nop 0
	global_load_lds_dwordx4 v184, s[14:15]
	s_add_u32 s14, s20, 0x80000
	s_addc_u32 s15, s21, 0
	s_add_i32 s54, s55, s26
	s_mov_b32 m0, s54
	s_nop 0
	global_load_lds_dwordx4 v162, s[14:15]
	s_add_i32 m0, s54, 0x2000
	s_nop 0
	global_load_lds_dwordx4 v184, s[14:15]
	s_mov_b64 s[14:15], s[22:23]
	s_mov_b32 m0, s27
	s_nop 0
	global_load_lds_dwordx4 v1, s[14:15]
	s_mov_b32 m0, s28
	s_nop 0
	global_load_lds_dwordx4 v164, s[14:15]
	s_waitcnt vmcnt(8)
	s_waitcnt lgkmcnt(0)
	s_barrier
; #define PG8_STAGE(bufoff, gbase, voff) do { const char* gb_ = (const char*)(gbase); asm volatile("" : "+s"(gb_)); _Pragma("unroll") for (int _i = 0; _i < 2; ++_i) { unsigned vo_ = (voff)[_i]; asm volatile("" : "+v"(vo_));        \
;         __builtin_amdgcn_global_load_lds((const unsigned*)(gb_ + vo_), (PG8_LAS unsigned*)(lds + (bufoff) + ldsw + _i * 8192), 16, 0, 0); } } while (0)
; #define PG8_LDA(dst, b, h) do { _Pragma("unroll") for (int m = 0; m < 4; ++m) _Pragma("unroll") for (int k = 0; k < 2; ++k) dst[m][k] = *(const PG8_LAS bf16x8*)(lds + PG8_SA(b, h) + aoff + m * 2048 + k * 1024); } while (0)
; #define PG8_LDB(dst, b, h) do { _Pragma("unroll") for (int n = 0; n < 2; ++n) _Pragma("unroll") for (int k = 0; k < 2; ++k) dst[n][k] = *(const PG8_LAS bf16x8*)(lds + PG8_SB(b, h) + boff + n * 2048 + k * 1024); } while (0)
; #define PG8_WAIT_V(n) asm volatile("s_waitcnt vmcnt(" #n ")" ::: "memory")
; #define PG8_WAIT_L(n) asm volatile("s_waitcnt lgkmcnt(" #n ")" ::: "memory")
; #define PG8_BAR __builtin_amdgcn_s_barrier()
; #define PG8_SCHED __builtin_amdgcn_sched_barrier(0)
; template <class Epi, class Sched, bool ALIGN_EPI = false, bool SP2 = false>
; __device__ __forceinline__ void gemm_phase(PG8_LAS unsigned char* lds, const Gemm g, const Sched& S, const Epi& E) {
;     ...
;             if constexpr (SP2) {
;             PG8_LDB(B0, 0, 0); PG8_LDB(B1, 0, 1); PG8_SCHED; PG8_LDA(At, 0, 0); PG8_STAGE(PG8_SA(1, 1), a1 + hstep, voffA);
;             PG8_WAIT_V(8); PG8_WAIT_L(0); PG8_BAR; PG8_MMA(0, 0, At, B0); PG8_MMA(0, 1, At, B1); PG8_BAR; PG8_SCHED;
;             PG8_LDA(At, 0, 1); PG8_STAGE(PG8_SB(0, 0), b2, voffB); PG8_STAGE(PG8_SB(0, 1), b2 + hstep, voffB); PG8_STAGE(PG8_SA(0, 0), a2, voffA);
;             PG8_WAIT_V(8); PG8_WAIT_L(0); PG8_BAR; PG8_MMA(1, 0, At, B0); PG8_MMA(1, 1, At, B1); PG8_BAR; PG8_SCHED;
;             PG8_LDB(B0, 1, 0); PG8_LDB(B1, 1, 1); PG8_SCHED; PG8_LDA(At, 1, 0); PG8_STAGE(PG8_SA(0, 1), a2 + hstep, voffA);
;             PG8_WAIT_V(8); PG8_WAIT_L(0); PG8_BAR; PG8_MMA(0, 0, At, B0); PG8_MMA(0, 1, At, B1); PG8_BAR; PG8_SCHED;
;             PG8_LDA(At, 1, 1); PG8_STAGE(PG8_SB(1, 0), b3, voffB); PG8_STAGE(PG8_SB(1, 1), b3 + hstep, voffB); PG8_STAGE(PG8_SA(1, 0), a3, voffA);
;             PG8_WAIT_V(8); PG8_WAIT_L(0); PG8_BAR; PG8_MMA(1, 0, At, B0); PG8_MMA(1, 1, At, B1); PG8_BAR; PG8_SCHED;
	s_setprio 1
	s_waitcnt lgkmcnt(0)
	v_mfma_f32_16x16x32_bf16 v[62:65], v[82:85], v[248:251], v[62:65]
	v_mfma_f32_16x16x32_bf16 v[62:65], v[86:89], v[252:255], v[62:65]
	v_mfma_f32_16x16x32_bf16 v[46:49], v[82:85], v[194:197], v[46:49]
	v_mfma_f32_16x16x32_bf16 v[46:49], v[86:89], v[198:201], v[46:49]
	v_mfma_f32_16x16x32_bf16 v[30:33], v[82:85], v[202:205], v[30:33]
	v_mfma_f32_16x16x32_bf16 v[30:33], v[86:89], v[206:209], v[30:33]
	v_mfma_f32_16x16x32_bf16 v[14:17], v[82:85], v[210:213], v[14:17]
	v_mfma_f32_16x16x32_bf16 v[14:17], v[86:89], v[220:223], v[14:17]
	v_mfma_f32_16x16x32_bf16 v[58:61], v[90:93], v[248:251], v[58:61]
	v_mfma_f32_16x16x32_bf16 v[58:61], v[94:97], v[252:255], v[58:61]
	v_mfma_f32_16x16x32_bf16 v[42:45], v[90:93], v[194:197], v[42:45]
	v_mfma_f32_16x16x32_bf16 v[42:45], v[94:97], v[198:201], v[42:45]
	v_mfma_f32_16x16x32_bf16 v[26:29], v[90:93], v[202:205], v[26:29]
	v_mfma_f32_16x16x32_bf16 v[26:29], v[94:97], v[206:209], v[26:29]
	v_mfma_f32_16x16x32_bf16 v[10:13], v[90:93], v[210:213], v[10:13]
	v_mfma_f32_16x16x32_bf16 v[10:13], v[94:97], v[220:223], v[10:13]
	s_setprio 0
	s_setprio 1
	v_mfma_f32_16x16x32_bf16 v[54:57], v[146:149], v[248:251], v[54:57]
	v_mfma_f32_16x16x32_bf16 v[54:57], v[150:153], v[252:255], v[54:57]
	v_mfma_f32_16x16x32_bf16 v[38:41], v[146:149], v[194:197], v[38:41]
	v_mfma_f32_16x16x32_bf16 v[38:41], v[150:153], v[198:201], v[38:41]
	v_mfma_f32_16x16x32_bf16 v[22:25], v[146:149], v[202:205], v[22:25]
	v_mfma_f32_16x16x32_bf16 v[22:25], v[150:153], v[206:209], v[22:25]
	v_mfma_f32_16x16x32_bf16 v[6:9], v[146:149], v[210:213], v[6:9]
	v_mfma_f32_16x16x32_bf16 v[6:9], v[150:153], v[220:223], v[6:9]
	v_mfma_f32_16x16x32_bf16 v[50:53], v[154:157], v[248:251], v[50:53]
	v_mfma_f32_16x16x32_bf16 v[50:53], v[158:161], v[252:255], v[50:53]
	v_mfma_f32_16x16x32_bf16 v[34:37], v[154:157], v[194:197], v[34:37]
	v_mfma_f32_16x16x32_bf16 v[34:37], v[158:161], v[198:201], v[34:37]
	v_mfma_f32_16x16x32_bf16 v[18:21], v[154:157], v[202:205], v[18:21]
	v_mfma_f32_16x16x32_bf16 v[18:21], v[158:161], v[206:209], v[18:21]
	v_mfma_f32_16x16x32_bf16 v[2:5], v[154:157], v[210:213], v[2:5]
	v_mfma_f32_16x16x32_bf16 v[2:5], v[158:161], v[220:223], v[2:5]
	s_setprio 0
	s_barrier
	s_add_i32 s54, 0, 0x18000
	s_add_i32 s55, 0, 0x1c000
	ds_read_b128 v[82:85], v244 offset:32768
	ds_read_b128 v[86:89], v244 offset:33792
	ds_read_b128 v[90:93], v244 offset:34816
	ds_read_b128 v[94:97], v244 offset:35840
	ds_read_b128 v[146:149], v244 offset:49152
	ds_read_b128 v[150:153], v244 offset:50176
	ds_read_b128 v[154:157], v244 offset:51200
	ds_read_b128 v[158:161], v244 offset:52224
	s_add_u32 s14, s22, 0x80000
	s_addc_u32 s15, s23, 0
	s_mov_b32 m0, s29
	ds_read_b128 v[248:251], v188 offset:32768
	ds_read_b128 v[252:255], v188 offset:33792
	ds_read_b128 v[194:197], v188 offset:34816
	ds_read_b128 v[198:201], v188 offset:35840
	ds_read_b128 v[202:205], v188 offset:36864
	ds_read_b128 v[206:209], v188 offset:37888
	ds_read_b128 v[210:213], v188 offset:38912
	ds_read_b128 v[220:223], v188 offset:39936
	s_nop 0
	global_load_lds_dwordx4 v1, s[14:15]
	s_mov_b32 m0, s33
	s_nop 0
	global_load_lds_dwordx4 v164, s[14:15]
	s_waitcnt vmcnt(8)
	s_waitcnt lgkmcnt(0)
	s_barrier
	s_setprio 1
	s_waitcnt lgkmcnt(0)
	v_mfma_f32_16x16x32_bf16 v[142:145], v[82:85], v[248:251], v[142:145]
	v_mfma_f32_16x16x32_bf16 v[142:145], v[86:89], v[252:255], v[142:145]
	v_mfma_f32_16x16x32_bf16 v[126:129], v[82:85], v[194:197], v[126:129]
	v_mfma_f32_16x16x32_bf16 v[126:129], v[86:89], v[198:201], v[126:129]
	v_mfma_f32_16x16x32_bf16 v[110:113], v[82:85], v[202:205], v[110:113]
	v_mfma_f32_16x16x32_bf16 v[110:113], v[86:89], v[206:209], v[110:113]
	v_mfma_f32_16x16x32_bf16 v[78:81], v[82:85], v[210:213], v[78:81]
	v_mfma_f32_16x16x32_bf16 v[78:81], v[86:89], v[220:223], v[78:81]
	v_mfma_f32_16x16x32_bf16 v[138:141], v[90:93], v[248:251], v[138:141]
	v_mfma_f32_16x16x32_bf16 v[138:141], v[94:97], v[252:255], v[138:141]
	v_mfma_f32_16x16x32_bf16 v[122:125], v[90:93], v[194:197], v[122:125]
	v_mfma_f32_16x16x32_bf16 v[122:125], v[94:97], v[198:201], v[122:125]
	v_mfma_f32_16x16x32_bf16 v[106:109], v[90:93], v[202:205], v[106:109]
	v_mfma_f32_16x16x32_bf16 v[106:109], v[94:97], v[206:209], v[106:109]
	v_mfma_f32_16x16x32_bf16 v[74:77], v[90:93], v[210:213], v[74:77]
	v_mfma_f32_16x16x32_bf16 v[74:77], v[94:97], v[220:223], v[74:77]
	s_setprio 0
	s_setprio 1
	v_mfma_f32_16x16x32_bf16 v[134:137], v[146:149], v[248:251], v[134:137]
	v_mfma_f32_16x16x32_bf16 v[134:137], v[150:153], v[252:255], v[134:137]
	v_mfma_f32_16x16x32_bf16 v[118:121], v[146:149], v[194:197], v[118:121]
	v_mfma_f32_16x16x32_bf16 v[118:121], v[150:153], v[198:201], v[118:121]
	v_mfma_f32_16x16x32_bf16 v[102:105], v[146:149], v[202:205], v[102:105]
	v_mfma_f32_16x16x32_bf16 v[102:105], v[150:153], v[206:209], v[102:105]
	v_mfma_f32_16x16x32_bf16 v[70:73], v[146:149], v[210:213], v[70:73]
	v_mfma_f32_16x16x32_bf16 v[70:73], v[150:153], v[220:223], v[70:73]
	v_mfma_f32_16x16x32_bf16 v[130:133], v[154:157], v[248:251], v[130:133]
	v_mfma_f32_16x16x32_bf16 v[130:133], v[158:161], v[252:255], v[130:133]
	v_mfma_f32_16x16x32_bf16 v[114:117], v[154:157], v[194:197], v[114:117]
	v_mfma_f32_16x16x32_bf16 v[114:117], v[158:161], v[198:201], v[114:117]
	v_mfma_f32_16x16x32_bf16 v[98:101], v[154:157], v[202:205], v[98:101]
	v_mfma_f32_16x16x32_bf16 v[98:101], v[158:161], v[206:209], v[98:101]
	v_mfma_f32_16x16x32_bf16 v[66:69], v[154:157], v[210:213], v[66:69]
	v_mfma_f32_16x16x32_bf16 v[66:69], v[158:161], v[220:223], v[66:69]
	s_setprio 0
	s_barrier
; #define PG8_STAGE(bufoff, gbase, voff) do { const char* gb_ = (const char*)(gbase); asm volatile("" : "+s"(gb_)); _Pragma("unroll") for (int _i = 0; _i < 2; ++_i) { unsigned vo_ = (voff)[_i]; asm volatile("" : "+v"(vo_));        \
;         __builtin_amdgcn_global_load_lds((const unsigned*)(gb_ + vo_), (PG8_LAS unsigned*)(lds + (bufoff) + ldsw + _i * 8192), 16, 0, 0); } } while (0)
; #define PG8_LDA(dst, b, h) do { _Pragma("unroll") for (int m = 0; m < 4; ++m) _Pragma("unroll") for (int k = 0; k < 2; ++k) dst[m][k] = *(const PG8_LAS bf16x8*)(lds + PG8_SA(b, h) + aoff + m * 2048 + k * 1024); } while (0)
; #define PG8_LDB(dst, b, h) do { _Pragma("unroll") for (int n = 0; n < 2; ++n) _Pragma("unroll") for (int k = 0; k < 2; ++k) dst[n][k] = *(const PG8_LAS bf16x8*)(lds + PG8_SB(b, h) + boff + n * 2048 + k * 1024); } while (0)
; #define PG8_WAIT_V(n) asm volatile("s_waitcnt vmcnt(" #n ")" ::: "memory")
; #define PG8_WAIT_L(n) asm volatile("s_waitcnt lgkmcnt(" #n ")" ::: "memory")
; #define PG8_BAR __builtin_amdgcn_s_barrier()
; #define PG8_SCHED __builtin_amdgcn_sched_barrier(0)
; template <class Epi, class Sched, bool ALIGN_EPI = false, bool SP2 = false>
; __device__ __forceinline__ void gemm_phase(PG8_LAS unsigned char* lds, const Gemm g, const Sched& S, const Epi& E) {
;     ...
;             if constexpr (SP2) {
;             PG8_LDB(B0, 0, 0); PG8_LDB(B1, 0, 1); PG8_SCHED; PG8_LDA(At, 0, 0); PG8_STAGE(PG8_SA(1, 1), a1 + hstep, voffA);
;             PG8_WAIT_V(8); PG8_WAIT_L(0); PG8_BAR; PG8_MMA(0, 0, At, B0); PG8_MMA(0, 1, At, B1); PG8_BAR; PG8_SCHED;
;             PG8_LDA(At, 0, 1); PG8_STAGE(PG8_SB(0, 0), b2, voffB); PG8_STAGE(PG8_SB(0, 1), b2 + hstep, voffB); PG8_STAGE(PG8_SA(0, 0), a2, voffA);
;             PG8_WAIT_V(8); PG8_WAIT_L(0); PG8_BAR; PG8_MMA(1, 0, At, B0); PG8_MMA(1, 1, At, B1); PG8_BAR; PG8_SCHED;
;             PG8_LDB(B0, 1, 0); PG8_LDB(B1, 1, 1); PG8_SCHED; PG8_LDA(At, 1, 0); PG8_STAGE(PG8_SA(0, 1), a2 + hstep, voffA);
;             PG8_WAIT_V(8); PG8_WAIT_L(0); PG8_BAR; PG8_MMA(0, 0, At, B0); PG8_MMA(0, 1, At, B1); PG8_BAR; PG8_SCHED;
;             PG8_LDA(At, 1, 1); PG8_STAGE(PG8_SB(1, 0), b3, voffB); PG8_STAGE(PG8_SB(1, 1), b3 + hstep, voffB); PG8_STAGE(PG8_SA(1, 0), a3, voffA);
;             PG8_WAIT_V(8); PG8_WAIT_L(0); PG8_BAR; PG8_MMA(1, 0, At, B0); PG8_MMA(1, 1, At, B1); PG8_BAR; PG8_SCHED;
	s_add_u32 s14, s20, 0x80
	s_addc_u32 s15, s21, 0
	s_add_i32 s22, s54, s26
	ds_read_b128 v[248:251], v188 offset:49152
	ds_read_b128 v[252:255], v188 offset:50176
	ds_read_b128 v[194:197], v188 offset:51200
	ds_read_b128 v[198:201], v188 offset:52224
	ds_read_b128 v[202:205], v188 offset:53248
	ds_read_b128 v[206:209], v188 offset:54272
	ds_read_b128 v[210:213], v188 offset:55296
	ds_read_b128 v[220:223], v188 offset:56320
	s_mov_b32 m0, s22
	s_nop 0
	global_load_lds_dwordx4 v162, s[14:15]
	s_add_i32 m0, s22, 0x2000
	s_nop 0
	global_load_lds_dwordx4 v184, s[14:15]
	s_add_u32 s14, s20, 0x80080
	s_addc_u32 s15, s21, 0
	s_add_i32 s20, s55, s26
	s_mov_b32 m0, s20
	s_nop 0
	global_load_lds_dwordx4 v162, s[14:15]
	s_add_i32 m0, s20, 0x2000
	s_nop 0
	global_load_lds_dwordx4 v184, s[14:15]
	s_mov_b32 m0, s38
	s_nop 0
	global_load_lds_dwordx4 v1, s[18:19]
	s_mov_b32 m0, s39
	s_nop 0
	global_load_lds_dwordx4 v164, s[18:19]
	s_waitcnt vmcnt(8)
	s_waitcnt lgkmcnt(0)
	s_barrier
	s_setprio 1
	s_waitcnt lgkmcnt(0)
	v_mfma_f32_16x16x32_bf16 v[62:65], v[82:85], v[248:251], v[62:65]
	v_mfma_f32_16x16x32_bf16 v[62:65], v[86:89], v[252:255], v[62:65]
	v_mfma_f32_16x16x32_bf16 v[46:49], v[82:85], v[194:197], v[46:49]
	v_mfma_f32_16x16x32_bf16 v[46:49], v[86:89], v[198:201], v[46:49]
	v_mfma_f32_16x16x32_bf16 v[30:33], v[82:85], v[202:205], v[30:33]
	v_mfma_f32_16x16x32_bf16 v[30:33], v[86:89], v[206:209], v[30:33]
	v_mfma_f32_16x16x32_bf16 v[14:17], v[82:85], v[210:213], v[14:17]
	v_mfma_f32_16x16x32_bf16 v[14:17], v[86:89], v[220:223], v[14:17]
	v_mfma_f32_16x16x32_bf16 v[58:61], v[90:93], v[248:251], v[58:61]
	v_mfma_f32_16x16x32_bf16 v[58:61], v[94:97], v[252:255], v[58:61]
	v_mfma_f32_16x16x32_bf16 v[42:45], v[90:93], v[194:197], v[42:45]
	v_mfma_f32_16x16x32_bf16 v[42:45], v[94:97], v[198:201], v[42:45]
	v_mfma_f32_16x16x32_bf16 v[26:29], v[90:93], v[202:205], v[26:29]
	v_mfma_f32_16x16x32_bf16 v[26:29], v[94:97], v[206:209], v[26:29]
	v_mfma_f32_16x16x32_bf16 v[10:13], v[90:93], v[210:213], v[10:13]
	v_mfma_f32_16x16x32_bf16 v[10:13], v[94:97], v[220:223], v[10:13]
	s_setprio 0
	s_setprio 1
	v_mfma_f32_16x16x32_bf16 v[54:57], v[146:149], v[248:251], v[54:57]
	v_mfma_f32_16x16x32_bf16 v[54:57], v[150:153], v[252:255], v[54:57]
	v_mfma_f32_16x16x32_bf16 v[38:41], v[146:149], v[194:197], v[38:41]
	v_mfma_f32_16x16x32_bf16 v[38:41], v[150:153], v[198:201], v[38:41]
	v_mfma_f32_16x16x32_bf16 v[22:25], v[146:149], v[202:205], v[22:25]
	v_mfma_f32_16x16x32_bf16 v[22:25], v[150:153], v[206:209], v[22:25]
	v_mfma_f32_16x16x32_bf16 v[6:9], v[146:149], v[210:213], v[6:9]
	v_mfma_f32_16x16x32_bf16 v[6:9], v[150:153], v[220:223], v[6:9]
	v_mfma_f32_16x16x32_bf16 v[50:53], v[154:157], v[248:251], v[50:53]
	v_mfma_f32_16x16x32_bf16 v[50:53], v[158:161], v[252:255], v[50:53]
	v_mfma_f32_16x16x32_bf16 v[34:37], v[154:157], v[194:197], v[34:37]
	v_mfma_f32_16x16x32_bf16 v[34:37], v[158:161], v[198:201], v[34:37]
	v_mfma_f32_16x16x32_bf16 v[18:21], v[154:157], v[202:205], v[18:21]
	v_mfma_f32_16x16x32_bf16 v[18:21], v[158:161], v[206:209], v[18:21]
	v_mfma_f32_16x16x32_bf16 v[2:5], v[154:157], v[210:213], v[2:5]
	v_mfma_f32_16x16x32_bf16 v[2:5], v[158:161], v[220:223], v[2:5]
	s_setprio 0
	s_barrier
	s_add_i32 s53, s53, 2
	s_add_u32 s51, s51, 0x100
	s_addc_u32 s52, s52, 0
	s_cmp_gt_u32 s53, 29
	s_mov_b64 s[14:15], s[16:17]
	s_cbranch_scc0 .LBB0_634
	s_and_b64 vcc, exec, s[2:3]
	s_cbranch_vccz .LBB0_637
	s_barrier

; #define PG8_STAGE(bufoff, gbase, voff) do { const char* gb_ = (const char*)(gbase); asm volatile("" : "+s"(gb_)); _Pragma("unroll") for (int _i = 0; _i < 2; ++_i) { unsigned vo_ = (voff)[_i]; asm volatile("" : "+v"(vo_));        \
;         __builtin_amdgcn_global_load_lds((const unsigned*)(gb_ + vo_), (PG8_LAS unsigned*)(lds + (bufoff) + ldsw + _i * 8192), 16, 0, 0); } } while (0)
; #define PG8_LDA(dst, b, h) do { _Pragma("unroll") for (int m = 0; m < 4; ++m) _Pragma("unroll") for (int k = 0; k < 2; ++k) dst[m][k] = *(const PG8_LAS bf16x8*)(lds + PG8_SA(b, h) + aoff + m * 2048 + k * 1024); } while (0)
; #define PG8_LDB(dst, b, h) do { _Pragma("unroll") for (int n = 0; n < 2; ++n) _Pragma("unroll") for (int k = 0; k < 2; ++k) dst[n][k] = *(const PG8_LAS bf16x8*)(lds + PG8_SB(b, h) + boff + n * 2048 + k * 1024); } while (0)
; #define PG8_WAIT_V(n) asm volatile("s_waitcnt vmcnt(" #n ")" ::: "memory")
; #define PG8_WAIT_L(n) asm volatile("s_waitcnt lgkmcnt(" #n ")" ::: "memory")
; #define PG8_BAR __builtin_amdgcn_s_barrier()
; #define PG8_SCHED __builtin_amdgcn_sched_barrier(0)
; template <class Epi, class Sched, bool ALIGN_EPI = false, bool SP2 = false>
; __device__ __forceinline__ void gemm_phase(PG8_LAS unsigned char* lds, const Gemm g, const Sched& S, const Epi& E) {
;     ...
;             if constexpr (SP2) {
;             PG8_LDB(B0, 0, 0); PG8_LDB(B1, 0, 1); PG8_SCHED; PG8_LDA(At, 0, 0); PG8_STAGE(PG8_SA(1, 1), a1 + hstep, voffA);
;             PG8_WAIT_V(8); PG8_WAIT_L(0); PG8_BAR; PG8_MMA(0, 0, At, B0); PG8_MMA(0, 1, At, B1); PG8_BAR; PG8_SCHED;
;             PG8_LDA(At, 0, 1); PG8_STAGE(PG8_SB(0, 0), b2, voffB); PG8_STAGE(PG8_SB(0, 1), b2 + hstep, voffB); PG8_STAGE(PG8_SA(0, 0), a2, voffA);
;             PG8_WAIT_V(8); PG8_WAIT_L(0); PG8_BAR; PG8_MMA(1, 0, At, B0); PG8_MMA(1, 1, At, B1); PG8_BAR; PG8_SCHED;
;             PG8_LDB(B0, 1, 0); PG8_LDB(B1, 1, 1); PG8_SCHED; PG8_LDA(At, 1, 0); PG8_STAGE(PG8_SA(0, 1), a2 + hstep, voffA);
;             PG8_WAIT_V(8); PG8_WAIT_L(0); PG8_BAR; PG8_MMA(0, 0, At, B0); PG8_MMA(0, 1, At, B1); PG8_BAR; PG8_SCHED;
;             PG8_LDA(At, 1, 1); PG8_STAGE(PG8_SB(1, 0), b3, voffB); PG8_STAGE(PG8_SB(1, 1), b3 + hstep, voffB); PG8_STAGE(PG8_SA(1, 0), a3, voffA);
;             PG8_WAIT_V(8); PG8_WAIT_L(0); PG8_BAR; PG8_MMA(1, 0, At, B0); PG8_MMA(1, 1, At, B1); PG8_BAR; PG8_SCHED;
.LBB0_707:
	s_add_u32 s2, s4, 0x100
	s_addc_u32 s3, s5, 0
	s_cmpk_eq_i32 s35, 0x54
	s_cselect_b32 s10, s52, s2
	s_cselect_b32 s11, s53, s3
	s_cselect_b32 s8, s42, s31
	s_cselect_b32 s9, s43, s34
	s_add_u32 s6, s10, 0x80
	s_addc_u32 s7, s11, 0
	s_add_i32 s38, 0, 0x10000
	s_add_i32 s39, 0, 0x14000
	ds_read_b128 v[34:37], v244
	ds_read_b128 v[38:41], v244 offset:1024
	ds_read_b128 v[98:101], v244 offset:2048
	ds_read_b128 v[102:105], v244 offset:3072
	ds_read_b128 v[146:149], v244 offset:16384
	ds_read_b128 v[150:153], v244 offset:17408
	ds_read_b128 v[154:157], v244 offset:18432
	ds_read_b128 v[158:161], v244 offset:19456
	s_add_u32 s4, s4, 0x160080
	s_addc_u32 s5, s5, 0
	ds_read_b128 v[248:251], v194
	ds_read_b128 v[252:255], v194 offset:1024
	ds_read_b128 v[186:189], v194 offset:2048
	ds_read_b128 v[196:199], v194 offset:3072
	ds_read_b128 v[200:203], v194 offset:4096
	ds_read_b128 v[204:207], v194 offset:5120
	ds_read_b128 v[208:211], v194 offset:6144
	ds_read_b128 v[212:215], v194 offset:7168
	s_add_i32 m0, s16, 0xc000
	s_nop 0
	global_load_lds_dwordx4 v1, s[4:5]
	s_add_i32 m0, s16, 0xe000
	s_nop 0
	global_load_lds_dwordx4 v164, s[4:5]
	s_waitcnt vmcnt(8)
	s_waitcnt lgkmcnt(0)
	s_barrier
	s_setprio 1
	s_waitcnt lgkmcnt(0)
	v_mfma_f32_16x16x32_bf16 v[142:145], v[34:37], v[248:251], v[142:145]
	v_mfma_f32_16x16x32_bf16 v[142:145], v[38:41], v[252:255], v[142:145]
	v_mfma_f32_16x16x32_bf16 v[134:137], v[34:37], v[186:189], v[134:137]
	v_mfma_f32_16x16x32_bf16 v[134:137], v[38:41], v[196:199], v[134:137]
	v_mfma_f32_16x16x32_bf16 v[126:129], v[34:37], v[200:203], v[126:129]
	v_mfma_f32_16x16x32_bf16 v[126:129], v[38:41], v[204:207], v[126:129]
	v_mfma_f32_16x16x32_bf16 v[118:121], v[34:37], v[208:211], v[118:121]
	v_mfma_f32_16x16x32_bf16 v[118:121], v[38:41], v[212:215], v[118:121]
	v_mfma_f32_16x16x32_bf16 v[138:141], v[98:101], v[248:251], v[138:141]
	v_mfma_f32_16x16x32_bf16 v[138:141], v[102:105], v[252:255], v[138:141]
	v_mfma_f32_16x16x32_bf16 v[130:133], v[98:101], v[186:189], v[130:133]
	v_mfma_f32_16x16x32_bf16 v[130:133], v[102:105], v[196:199], v[130:133]
	v_mfma_f32_16x16x32_bf16 v[122:125], v[98:101], v[200:203], v[122:125]
	v_mfma_f32_16x16x32_bf16 v[122:125], v[102:105], v[204:207], v[122:125]
	v_mfma_f32_16x16x32_bf16 v[114:117], v[98:101], v[208:211], v[114:117]
	v_mfma_f32_16x16x32_bf16 v[114:117], v[102:105], v[212:215], v[114:117]
	s_setprio 0
	s_setprio 1
	v_mfma_f32_16x16x32_bf16 v[70:73], v[146:149], v[248:251], v[70:73]
	v_mfma_f32_16x16x32_bf16 v[70:73], v[150:153], v[252:255], v[70:73]
	v_mfma_f32_16x16x32_bf16 v[62:65], v[146:149], v[186:189], v[62:65]
	v_mfma_f32_16x16x32_bf16 v[62:65], v[150:153], v[196:199], v[62:65]
	v_mfma_f32_16x16x32_bf16 v[54:57], v[146:149], v[200:203], v[54:57]
	v_mfma_f32_16x16x32_bf16 v[54:57], v[150:153], v[204:207], v[54:57]
	v_mfma_f32_16x16x32_bf16 v[46:49], v[146:149], v[208:211], v[46:49]
	v_mfma_f32_16x16x32_bf16 v[46:49], v[150:153], v[212:215], v[46:49]
	v_mfma_f32_16x16x32_bf16 v[66:69], v[154:157], v[248:251], v[66:69]
	v_mfma_f32_16x16x32_bf16 v[66:69], v[158:161], v[252:255], v[66:69]
	v_mfma_f32_16x16x32_bf16 v[58:61], v[154:157], v[186:189], v[58:61]
	v_mfma_f32_16x16x32_bf16 v[58:61], v[158:161], v[196:199], v[58:61]
	v_mfma_f32_16x16x32_bf16 v[50:53], v[154:157], v[200:203], v[50:53]
	v_mfma_f32_16x16x32_bf16 v[50:53], v[158:161], v[204:207], v[50:53]
	v_mfma_f32_16x16x32_bf16 v[42:45], v[154:157], v[208:211], v[42:45]
	v_mfma_f32_16x16x32_bf16 v[42:45], v[158:161], v[212:215], v[42:45]
	s_setprio 0
	s_barrier
	s_mov_b64 s[4:5], s[8:9]
	s_add_i32 s38, s38, s15
	ds_read_b128 v[248:251], v194 offset:16384
	ds_read_b128 v[252:255], v194 offset:17408
	ds_read_b128 v[186:189], v194 offset:18432
	ds_read_b128 v[196:199], v194 offset:19456
	ds_read_b128 v[200:203], v194 offset:20480
	ds_read_b128 v[204:207], v194 offset:21504
	ds_read_b128 v[208:211], v194 offset:22528
	ds_read_b128 v[212:215], v194 offset:23552
	s_mov_b32 m0, s38
	s_nop 0
	global_load_lds_dwordx4 v162, s[4:5]
	s_add_i32 m0, s38, 0x2000
	s_nop 0
	global_load_lds_dwordx4 v190, s[4:5]
	s_add_u32 s4, s8, 0x160000
	s_addc_u32 s5, s9, 0
	s_add_i32 s38, s39, s15
	s_mov_b32 m0, s38
	s_nop 0
	global_load_lds_dwordx4 v162, s[4:5]
	s_add_i32 m0, s38, 0x2000
	s_nop 0
	global_load_lds_dwordx4 v190, s[4:5]
	s_mov_b64 s[4:5], s[10:11]
	s_mov_b32 m0, s16
	s_nop 0
	global_load_lds_dwordx4 v1, s[4:5]
	s_mov_b32 m0, s17
	s_nop 0
	global_load_lds_dwordx4 v164, s[4:5]
	s_waitcnt vmcnt(8)
	s_waitcnt lgkmcnt(0)
	s_barrier
; #define PG8_STAGE(bufoff, gbase, voff) do { const char* gb_ = (const char*)(gbase); asm volatile("" : "+s"(gb_)); _Pragma("unroll") for (int _i = 0; _i < 2; ++_i) { unsigned vo_ = (voff)[_i]; asm volatile("" : "+v"(vo_));        \
;         __builtin_amdgcn_global_load_lds((const unsigned*)(gb_ + vo_), (PG8_LAS unsigned*)(lds + (bufoff) + ldsw + _i * 8192), 16, 0, 0); } } while (0)
; #define PG8_LDA(dst, b, h) do { _Pragma("unroll") for (int m = 0; m < 4; ++m) _Pragma("unroll") for (int k = 0; k < 2; ++k) dst[m][k] = *(const PG8_LAS bf16x8*)(lds + PG8_SA(b, h) + aoff + m * 2048 + k * 1024); } while (0)
; #define PG8_LDB(dst, b, h) do { _Pragma("unroll") for (int n = 0; n < 2; ++n) _Pragma("unroll") for (int k = 0; k < 2; ++k) dst[n][k] = *(const PG8_LAS bf16x8*)(lds + PG8_SB(b, h) + boff + n * 2048 + k * 1024); } while (0)
; #define PG8_WAIT_V(n) asm volatile("s_waitcnt vmcnt(" #n ")" ::: "memory")
; #define PG8_WAIT_L(n) asm volatile("s_waitcnt lgkmcnt(" #n ")" ::: "memory")
; #define PG8_BAR __builtin_amdgcn_s_barrier()
; #define PG8_SCHED __builtin_amdgcn_sched_barrier(0)
; template <class Epi, class Sched, bool ALIGN_EPI = false, bool SP2 = false>
; __device__ __forceinline__ void gemm_phase(PG8_LAS unsigned char* lds, const Gemm g, const Sched& S, const Epi& E) {
;     ...
;             if constexpr (SP2) {
;             PG8_LDB(B0, 0, 0); PG8_LDB(B1, 0, 1); PG8_SCHED; PG8_LDA(At, 0, 0); PG8_STAGE(PG8_SA(1, 1), a1 + hstep, voffA);
;             PG8_WAIT_V(8); PG8_WAIT_L(0); PG8_BAR; PG8_MMA(0, 0, At, B0); PG8_MMA(0, 1, At, B1); PG8_BAR; PG8_SCHED;
;             PG8_LDA(At, 0, 1); PG8_STAGE(PG8_SB(0, 0), b2, voffB); PG8_STAGE(PG8_SB(0, 1), b2 + hstep, voffB); PG8_STAGE(PG8_SA(0, 0), a2, voffA);
;             PG8_WAIT_V(8); PG8_WAIT_L(0); PG8_BAR; PG8_MMA(1, 0, At, B0); PG8_MMA(1, 1, At, B1); PG8_BAR; PG8_SCHED;
;             PG8_LDB(B0, 1, 0); PG8_LDB(B1, 1, 1); PG8_SCHED; PG8_LDA(At, 1, 0); PG8_STAGE(PG8_SA(0, 1), a2 + hstep, voffA);
;             PG8_WAIT_V(8); PG8_WAIT_L(0); PG8_BAR; PG8_MMA(0, 0, At, B0); PG8_MMA(0, 1, At, B1); PG8_BAR; PG8_SCHED;
;             PG8_LDA(At, 1, 1); PG8_STAGE(PG8_SB(1, 0), b3, voffB); PG8_STAGE(PG8_SB(1, 1), b3 + hstep, voffB); PG8_STAGE(PG8_SA(1, 0), a3, voffA);
;             PG8_WAIT_V(8); PG8_WAIT_L(0); PG8_BAR; PG8_MMA(1, 0, At, B0); PG8_MMA(1, 1, At, B1); PG8_BAR; PG8_SCHED;
	s_setprio 1
	s_waitcnt lgkmcnt(0)
	v_mfma_f32_16x16x32_bf16 v[110:113], v[34:37], v[248:251], v[110:113]
	v_mfma_f32_16x16x32_bf16 v[110:113], v[38:41], v[252:255], v[110:113]
	v_mfma_f32_16x16x32_bf16 v[94:97], v[34:37], v[186:189], v[94:97]
	v_mfma_f32_16x16x32_bf16 v[94:97], v[38:41], v[196:199], v[94:97]
	v_mfma_f32_16x16x32_bf16 v[86:89], v[34:37], v[200:203], v[86:89]
	v_mfma_f32_16x16x32_bf16 v[86:89], v[38:41], v[204:207], v[86:89]
	v_mfma_f32_16x16x32_bf16 v[34:37], v[34:37], v[208:211], v[78:81]
	v_mfma_f32_16x16x32_bf16 v[34:37], v[38:41], v[212:215], v[34:37]
	v_mfma_f32_16x16x32_bf16 v[106:109], v[98:101], v[248:251], v[106:109]
	v_mfma_f32_16x16x32_bf16 v[106:109], v[102:105], v[252:255], v[106:109]
	v_mfma_f32_16x16x32_bf16 v[90:93], v[98:101], v[186:189], v[90:93]
	v_mfma_f32_16x16x32_bf16 v[90:93], v[102:105], v[196:199], v[90:93]
	v_mfma_f32_16x16x32_bf16 v[82:85], v[98:101], v[200:203], v[82:85]
	v_mfma_f32_16x16x32_bf16 v[82:85], v[102:105], v[204:207], v[82:85]
	v_mfma_f32_16x16x32_bf16 v[38:41], v[98:101], v[208:211], v[74:77]
	v_mfma_f32_16x16x32_bf16 v[38:41], v[102:105], v[212:215], v[38:41]
	s_setprio 0
	s_setprio 1
	v_mfma_f32_16x16x32_bf16 v[30:33], v[146:149], v[248:251], v[30:33]
	v_mfma_f32_16x16x32_bf16 v[30:33], v[150:153], v[252:255], v[30:33]
	v_mfma_f32_16x16x32_bf16 v[22:25], v[146:149], v[186:189], v[22:25]
	v_mfma_f32_16x16x32_bf16 v[22:25], v[150:153], v[196:199], v[22:25]
	v_mfma_f32_16x16x32_bf16 v[14:17], v[146:149], v[200:203], v[14:17]
	v_mfma_f32_16x16x32_bf16 v[14:17], v[150:153], v[204:207], v[14:17]
	v_mfma_f32_16x16x32_bf16 v[6:9], v[146:149], v[208:211], v[6:9]
	v_mfma_f32_16x16x32_bf16 v[6:9], v[150:153], v[212:215], v[6:9]
	v_mfma_f32_16x16x32_bf16 v[26:29], v[154:157], v[248:251], v[26:29]
	v_mfma_f32_16x16x32_bf16 v[26:29], v[158:161], v[252:255], v[26:29]
	v_mfma_f32_16x16x32_bf16 v[18:21], v[154:157], v[186:189], v[18:21]
	v_mfma_f32_16x16x32_bf16 v[18:21], v[158:161], v[196:199], v[18:21]
	v_mfma_f32_16x16x32_bf16 v[10:13], v[154:157], v[200:203], v[10:13]
	v_mfma_f32_16x16x32_bf16 v[10:13], v[158:161], v[204:207], v[10:13]
	v_mfma_f32_16x16x32_bf16 v[2:5], v[154:157], v[208:211], v[2:5]
	v_mfma_f32_16x16x32_bf16 v[2:5], v[158:161], v[212:215], v[2:5]
	s_setprio 0
	s_barrier
	s_add_i32 s38, 0, 0x18000
	s_add_i32 s39, 0, 0x1c000
	ds_read_b128 v[74:77], v244 offset:32768
	ds_read_b128 v[78:81], v244 offset:33792
	ds_read_b128 v[98:101], v244 offset:34816
	ds_read_b128 v[102:105], v244 offset:35840
	ds_read_b128 v[146:149], v244 offset:49152
	ds_read_b128 v[150:153], v244 offset:50176
	ds_read_b128 v[154:157], v244 offset:51200
	ds_read_b128 v[158:161], v244 offset:52224
	s_add_u32 s4, s10, 0x160000
	s_addc_u32 s5, s11, 0
	s_mov_b32 m0, s18
	ds_read_b128 v[248:251], v194 offset:32768
	ds_read_b128 v[252:255], v194 offset:33792
	ds_read_b128 v[186:189], v194 offset:34816
	ds_read_b128 v[196:199], v194 offset:35840
	ds_read_b128 v[200:203], v194 offset:36864
	ds_read_b128 v[204:207], v194 offset:37888
	ds_read_b128 v[208:211], v194 offset:38912
	ds_read_b128 v[212:215], v194 offset:39936
	s_nop 0
	global_load_lds_dwordx4 v1, s[4:5]
	s_mov_b32 m0, s19
	s_nop 0
	global_load_lds_dwordx4 v164, s[4:5]
	s_waitcnt vmcnt(8)
	s_waitcnt lgkmcnt(0)
	s_barrier
	s_setprio 1
	s_waitcnt lgkmcnt(0)
	v_mfma_f32_16x16x32_bf16 v[142:145], v[74:77], v[248:251], v[142:145]
	v_mfma_f32_16x16x32_bf16 v[142:145], v[78:81], v[252:255], v[142:145]
	v_mfma_f32_16x16x32_bf16 v[134:137], v[74:77], v[186:189], v[134:137]
	v_mfma_f32_16x16x32_bf16 v[134:137], v[78:81], v[196:199], v[134:137]
	v_mfma_f32_16x16x32_bf16 v[126:129], v[74:77], v[200:203], v[126:129]
	v_mfma_f32_16x16x32_bf16 v[126:129], v[78:81], v[204:207], v[126:129]
	v_mfma_f32_16x16x32_bf16 v[118:121], v[74:77], v[208:211], v[118:121]
	v_mfma_f32_16x16x32_bf16 v[118:121], v[78:81], v[212:215], v[118:121]
	v_mfma_f32_16x16x32_bf16 v[138:141], v[98:101], v[248:251], v[138:141]
	v_mfma_f32_16x16x32_bf16 v[138:141], v[102:105], v[252:255], v[138:141]
	v_mfma_f32_16x16x32_bf16 v[130:133], v[98:101], v[186:189], v[130:133]
	v_mfma_f32_16x16x32_bf16 v[130:133], v[102:105], v[196:199], v[130:133]
	v_mfma_f32_16x16x32_bf16 v[122:125], v[98:101], v[200:203], v[122:125]
	v_mfma_f32_16x16x32_bf16 v[122:125], v[102:105], v[204:207], v[122:125]
	v_mfma_f32_16x16x32_bf16 v[114:117], v[98:101], v[208:211], v[114:117]
	v_mfma_f32_16x16x32_bf16 v[114:117], v[102:105], v[212:215], v[114:117]
	s_setprio 0
	s_setprio 1
	v_mfma_f32_16x16x32_bf16 v[70:73], v[146:149], v[248:251], v[70:73]
	v_mfma_f32_16x16x32_bf16 v[70:73], v[150:153], v[252:255], v[70:73]
	v_mfma_f32_16x16x32_bf16 v[62:65], v[146:149], v[186:189], v[62:65]
	v_mfma_f32_16x16x32_bf16 v[62:65], v[150:153], v[196:199], v[62:65]
	v_mfma_f32_16x16x32_bf16 v[54:57], v[146:149], v[200:203], v[54:57]
	v_mfma_f32_16x16x32_bf16 v[54:57], v[150:153], v[204:207], v[54:57]
	v_mfma_f32_16x16x32_bf16 v[46:49], v[146:149], v[208:211], v[46:49]
	v_mfma_f32_16x16x32_bf16 v[46:49], v[150:153], v[212:215], v[46:49]
	v_mfma_f32_16x16x32_bf16 v[66:69], v[154:157], v[248:251], v[66:69]
	v_mfma_f32_16x16x32_bf16 v[66:69], v[158:161], v[252:255], v[66:69]
	v_mfma_f32_16x16x32_bf16 v[58:61], v[154:157], v[186:189], v[58:61]
	v_mfma_f32_16x16x32_bf16 v[58:61], v[158:161], v[196:199], v[58:61]
	v_mfma_f32_16x16x32_bf16 v[50:53], v[154:157], v[200:203], v[50:53]
	v_mfma_f32_16x16x32_bf16 v[50:53], v[158:161], v[204:207], v[50:53]
	v_mfma_f32_16x16x32_bf16 v[42:45], v[154:157], v[208:211], v[42:45]
	v_mfma_f32_16x16x32_bf16 v[42:45], v[158:161], v[212:215], v[42:45]
	s_setprio 0
	s_barrier
; #define PG8_WAIT_V(n) asm volatile("s_waitcnt vmcnt(" #n ")" ::: "memory")
;     __device__ __forceinline__ void operator()(const f32x4 (&acc)[2][2][4][2], const Unit& u, int wr, int wc, int fr, int fq) const {
;         const int row0 = u.pm * BM + wr * 64 + fr, col0 = u.pn * BM + wc * 32 + 8 * fq, b = (u.pm * BM) / rows_per_batch;
;         const float* g = gate + (size_t)b * gate_bstride + col0;
;         float ssq[2][4];
; #pragma unroll
;         for (int ai = 0; ai < 2; ++ai)
; #pragma unroll
;             for (int m = 0; m < 4; ++m) ssq[ai][m] = 0.f;
;         f32x4 gv[2][2], Gv[2][2];
; #pragma unroll
;         for (int bj = 0; bj < 2; ++bj) { gv[bj][0] = *(const f32x4*)(g + bj * HALF); gv[bj][1] = *(const f32x4*)(g + bj * HALF + 4); Gv[bj][0] = (f32x4){0.f, 0.f, 0.f, 0.f}; Gv[bj][1] = (f32x4){0.f, 0.f, 0.f, 0.f};
;             if (Hn) { const float* sc = scnext + (size_t)b * gate_bstride + col0 + bj * HALF;
;                 Gv[bj][0] = *(const f32x4*)(gnext + col0 + bj * HALF) * (1.0f + *(const f32x4*)(sc)); Gv[bj][1] = *(const f32x4*)(gnext + col0 + bj * HALF + 4) * (1.0f + *(const f32x4*)(sc + 4)); } }
; template <class Epi, class Sched, bool ALIGN_EPI = false, bool SP2 = false>
; __device__ __forceinline__ void gemm_phase(PG8_LAS unsigned char* lds, const Gemm g, const Sched& S, const Epi& E) {
;     ...
;             if constexpr (SP2) {
;             PG8_LDB(B0, 0, 0); PG8_LDB(B1, 0, 1); PG8_SCHED; PG8_LDA(At, 0, 0); PG8_STAGE(PG8_SA(1, 1), a1 + hstep, voffA);
;             PG8_WAIT_V(8); PG8_WAIT_L(0); PG8_BAR; PG8_MMA(0, 0, At, B0); PG8_MMA(0, 1, At, B1); PG8_BAR; PG8_SCHED;
;             PG8_LDA(At, 0, 1); PG8_STAGE(PG8_SB(0, 0), b2, voffB); PG8_STAGE(PG8_SB(0, 1), b2 + hstep, voffB); PG8_STAGE(PG8_SA(0, 0), a2, voffA);
;             PG8_WAIT_V(8); PG8_WAIT_L(0); PG8_BAR; PG8_MMA(1, 0, At, B0); PG8_MMA(1, 1, At, B1); PG8_BAR; PG8_SCHED;
;             PG8_LDB(B0, 1, 0); PG8_LDB(B1, 1, 1); PG8_SCHED; PG8_LDA(At, 1, 0); PG8_STAGE(PG8_SA(0, 1), a2 + hstep, voffA);
;             PG8_WAIT_V(8); PG8_WAIT_L(0); PG8_BAR; PG8_MMA(0, 0, At, B0); PG8_MMA(0, 1, At, B1); PG8_BAR; PG8_SCHED;
;             PG8_LDA(At, 1, 1); PG8_STAGE(PG8_SB(1, 0), b3, voffB); PG8_STAGE(PG8_SB(1, 1), b3 + hstep, voffB); PG8_STAGE(PG8_SA(1, 0), a3, voffA);
;             PG8_WAIT_V(8); PG8_WAIT_L(0); PG8_BAR; PG8_MMA(1, 0, At, B0); PG8_MMA(1, 1, At, B1); PG8_BAR; PG8_SCHED;
	s_add_u32 s4, s8, 0x80
	s_addc_u32 s5, s9, 0
	s_add_i32 s10, s38, s15
	ds_read_b128 v[248:251], v194 offset:49152
	ds_read_b128 v[252:255], v194 offset:50176
	ds_read_b128 v[186:189], v194 offset:51200
	ds_read_b128 v[196:199], v194 offset:52224
	ds_read_b128 v[200:203], v194 offset:53248
	ds_read_b128 v[204:207], v194 offset:54272
	ds_read_b128 v[208:211], v194 offset:55296
	ds_read_b128 v[212:215], v194 offset:56320
	s_mov_b32 m0, s10
	s_nop 0
	global_load_lds_dwordx4 v162, s[4:5]
	s_add_i32 m0, s10, 0x2000
	s_nop 0
	global_load_lds_dwordx4 v190, s[4:5]
	s_add_u32 s4, s8, 0x160080
	s_addc_u32 s5, s9, 0
	s_add_i32 s8, s39, s15
	s_mov_b32 m0, s8
	s_nop 0
	global_load_lds_dwordx4 v162, s[4:5]
	s_add_i32 m0, s8, 0x2000
	s_nop 0
	global_load_lds_dwordx4 v190, s[4:5]
	s_mov_b32 m0, s24
	s_nop 0
	global_load_lds_dwordx4 v1, s[6:7]
	s_mov_b32 m0, s25
	s_nop 0
	global_load_lds_dwordx4 v164, s[6:7]
	s_waitcnt vmcnt(8)
	s_waitcnt lgkmcnt(0)
	s_barrier
	s_setprio 1
	s_waitcnt lgkmcnt(0)
	v_mfma_f32_16x16x32_bf16 v[110:113], v[74:77], v[248:251], v[110:113]
	v_mfma_f32_16x16x32_bf16 v[110:113], v[78:81], v[252:255], v[110:113]
	v_mfma_f32_16x16x32_bf16 v[94:97], v[74:77], v[186:189], v[94:97]
	v_mfma_f32_16x16x32_bf16 v[94:97], v[78:81], v[196:199], v[94:97]
	v_mfma_f32_16x16x32_bf16 v[86:89], v[74:77], v[200:203], v[86:89]
	v_mfma_f32_16x16x32_bf16 v[86:89], v[78:81], v[204:207], v[86:89]
	v_mfma_f32_16x16x32_bf16 v[34:37], v[74:77], v[208:211], v[34:37]
	v_mfma_f32_16x16x32_bf16 v[78:81], v[78:81], v[212:215], v[34:37]
	v_mfma_f32_16x16x32_bf16 v[106:109], v[98:101], v[248:251], v[106:109]
	v_mfma_f32_16x16x32_bf16 v[106:109], v[102:105], v[252:255], v[106:109]
	v_mfma_f32_16x16x32_bf16 v[90:93], v[98:101], v[186:189], v[90:93]
	v_mfma_f32_16x16x32_bf16 v[90:93], v[102:105], v[196:199], v[90:93]
	v_mfma_f32_16x16x32_bf16 v[82:85], v[98:101], v[200:203], v[82:85]
	v_mfma_f32_16x16x32_bf16 v[82:85], v[102:105], v[204:207], v[82:85]
	v_mfma_f32_16x16x32_bf16 v[34:37], v[98:101], v[208:211], v[38:41]
	v_mfma_f32_16x16x32_bf16 v[74:77], v[102:105], v[212:215], v[34:37]
	s_setprio 0
	s_setprio 1
	v_mfma_f32_16x16x32_bf16 v[30:33], v[146:149], v[248:251], v[30:33]
	v_mfma_f32_16x16x32_bf16 v[30:33], v[150:153], v[252:255], v[30:33]
	v_mfma_f32_16x16x32_bf16 v[22:25], v[146:149], v[186:189], v[22:25]
	v_mfma_f32_16x16x32_bf16 v[22:25], v[150:153], v[196:199], v[22:25]
	v_mfma_f32_16x16x32_bf16 v[14:17], v[146:149], v[200:203], v[14:17]
	v_mfma_f32_16x16x32_bf16 v[14:17], v[150:153], v[204:207], v[14:17]
	v_mfma_f32_16x16x32_bf16 v[6:9], v[146:149], v[208:211], v[6:9]
	v_mfma_f32_16x16x32_bf16 v[6:9], v[150:153], v[212:215], v[6:9]
	v_mfma_f32_16x16x32_bf16 v[26:29], v[154:157], v[248:251], v[26:29]
	v_mfma_f32_16x16x32_bf16 v[26:29], v[158:161], v[252:255], v[26:29]
	v_mfma_f32_16x16x32_bf16 v[18:21], v[154:157], v[186:189], v[18:21]
	v_mfma_f32_16x16x32_bf16 v[18:21], v[158:161], v[196:199], v[18:21]
	v_mfma_f32_16x16x32_bf16 v[10:13], v[154:157], v[200:203], v[10:13]
	v_mfma_f32_16x16x32_bf16 v[10:13], v[158:161], v[204:207], v[10:13]
	v_mfma_f32_16x16x32_bf16 v[2:5], v[154:157], v[208:211], v[2:5]
	v_mfma_f32_16x16x32_bf16 v[2:5], v[158:161], v[212:215], v[2:5]
	s_setprio 0
	s_barrier
	s_add_i32 s35, s35, 2
	s_add_u32 s31, s31, 0x100
	s_addc_u32 s34, s34, 0
	s_cmpk_gt_u32 s35, 0x55
	s_mov_b64 s[4:5], s[2:3]
	s_cbranch_scc0 .LBB0_707
	s_ashr_i32 s2, s29, 31
	s_lshr_b32 s2, s2, 27
	s_add_i32 s2, s29, s2
	s_ashr_i32 s2, s2, 5
	v_lshl_or_b32 v156, s30, 8, v193
	s_mul_i32 s5, s2, 0xc000
	v_ashrrev_i32_e32 v157, 31, v156
	s_mul_hi_i32 s4, s2, 0xc000
	s_add_u32 s2, s20, s5
	s_addc_u32 s3, s21, s4
	v_lshlrev_b64 v[34:35], 2, v[156:157]
	v_lshl_add_u64 v[38:39], s[2:3], 0, v[34:35]
	global_load_dwordx4 v[98:101], v[38:39], off offset:16
	global_load_dwordx4 v[102:105], v[38:39], off
	s_add_u32 s2, s22, s5
	s_addc_u32 s3, s23, s4
	v_lshl_add_u64 v[148:149], s[2:3], 0, v[34:35]
	v_lshl_add_u64 v[146:147], s[48:49], 0, v[34:35]
	v_mov_b32_e32 v158, 0
	v_cndmask_b32_e64 v34, 0, 1, s[46:47]
	v_cmp_ne_u32_e64 s[2:3], 1, v34
	s_andn2_b64 vcc, exec, s[46:47]
	v_mov_b32_e32 v159, v158
	v_mov_b32_e32 v160, v158
	v_mov_b32_e32 v161, v158
	v_mov_b32_e32 v178, v158
	v_mov_b32_e32 v179, v158
	v_mov_b32_e32 v180, v158
	v_mov_b32_e32 v181, v158
	s_cbranch_vccnz .LBB0_710
	global_load_dwordx4 v[34:37], v[148:149], off
	global_load_dwordx4 v[150:153], v[148:149], off offset:16
	global_load_dwordx4 v[158:161], v[146:147], off
	global_load_dwordx4 v[178:181], v[146:147], off offset:16
	s_waitcnt vmcnt(0)
	v_pk_add_f32 v[36:37], v[36:37], 1.0 op_sel_hi:[1,0]
	v_pk_add_f32 v[34:35], v[34:35], 1.0 op_sel_hi:[1,0]
	v_pk_add_f32 v[40:41], v[152:153], 1.0 op_sel_hi:[1,0]
	v_pk_add_f32 v[150:151], v[150:151], 1.0 op_sel_hi:[1,0]
	v_pk_mul_f32 v[160:161], v[160:161], v[36:37]
	v_pk_mul_f32 v[158:159], v[158:159], v[34:35]
	v_pk_mul_f32 v[180:181], v[180:181], v[40:41]
	v_pk_mul_f32 v[178:179], v[178:179], v[150:151]

; __global__ void __launch_bounds__(NWAVES * 64, 2) skel_fwd(Args args) {
;     extern __shared__ __attribute__((aligned(16))) unsigned char lds[];
	.amdhsa_kernel _Z8skel_fwd4Args
		.amdhsa_group_segment_fixed_size 0
		.amdhsa_private_segment_fixed_size 0
		.amdhsa_kernarg_size 408
		.amdhsa_user_sgpr_count 2
		.amdhsa_user_sgpr_dispatch_ptr 0
		.amdhsa_user_sgpr_queue_ptr 0
		.amdhsa_user_sgpr_kernarg_segment_ptr 1
		.amdhsa_user_sgpr_dispatch_id 0
		.amdhsa_user_sgpr_kernarg_preload_length 0
		.amdhsa_user_sgpr_kernarg_preload_offset 0
		.amdhsa_user_sgpr_private_segment_size 0
		.amdhsa_uses_dynamic_stack 0
		.amdhsa_enable_private_segment 0
		.amdhsa_system_sgpr_workgroup_id_x 1
		.amdhsa_system_sgpr_workgroup_id_y 0
		.amdhsa_system_sgpr_workgroup_id_z 0
		.amdhsa_system_sgpr_workgroup_info 0
		.amdhsa_system_vgpr_workitem_id 0
		.amdhsa_next_free_vgpr 256
		.amdhsa_next_free_sgpr 98
		.amdhsa_accum_offset 256
		.amdhsa_reserve_vcc 1
		.amdhsa_float_round_mode_32 0
		.amdhsa_float_round_mode_16_64 0
		.amdhsa_float_denorm_mode_32 3
		.amdhsa_float_denorm_mode_16_64 3
		.amdhsa_dx10_clamp 1
		.amdhsa_ieee_mode 1
		.amdhsa_fp16_overflow 0
		.amdhsa_tg_split 0
		.amdhsa_exception_fp_ieee_invalid_op 0
		.amdhsa_exception_fp_denorm_src 0
		.amdhsa_exception_fp_ieee_div_zero 0
		.amdhsa_exception_fp_ieee_overflow 0
		.amdhsa_exception_fp_ieee_underflow 0
		.amdhsa_exception_fp_ieee_inexact 0
		.amdhsa_exception_int_div_zero 0
	.end_amdhsa_kernel

; __global__ void __launch_bounds__(NWAVES * 64, 2) skel_fwd(Args args) {
;     extern __shared__ __attribute__((aligned(16))) unsigned char lds[];
amdhsa.kernels:
  - .agpr_count:     0
    .args:
      - .offset:         0
        .size:           152
        .value_kind:     by_value
      - .offset:         152
        .size:           4
        .value_kind:     hidden_block_count_x
      - .offset:         156
        .size:           4
        .value_kind:     hidden_block_count_y
      - .offset:         160
        .size:           4
        .value_kind:     hidden_block_count_z
      - .offset:         164
        .size:           2
        .value_kind:     hidden_group_size_x
      - .offset:         166
        .size:           2
        .value_kind:     hidden_group_size_y
      - .offset:         168
        .size:           2
        .value_kind:     hidden_group_size_z
      - .offset:         170
        .size:           2
        .value_kind:     hidden_remainder_x
      - .offset:         172
        .size:           2
        .value_kind:     hidden_remainder_y
      - .offset:         174
        .size:           2
        .value_kind:     hidden_remainder_z
      - .offset:         192
        .size:           8
        .value_kind:     hidden_global_offset_x
      - .offset:         200
        .size:           8
        .value_kind:     hidden_global_offset_y
      - .offset:         208
        .size:           8
        .value_kind:     hidden_global_offset_z
      - .offset:         216
        .size:           2
        .value_kind:     hidden_grid_dims
      - .offset:         272
        .size:           4
        .value_kind:     hidden_dynamic_lds_size
    .group_segment_fixed_size: 0
    .kernarg_segment_align: 8
    .kernarg_segment_size: 408
    .language:       OpenCL C
    .language_version:
      - 2
      - 0
    .max_flat_workgroup_size: 512
    .name:           _Z8skel_fwd4Args
    .private_segment_fixed_size: 0
    .sgpr_count:     104
    .sgpr_spill_count: 247
    .symbol:         _Z8skel_fwd4Args.kd
    .uniform_work_group_size: 1
    .uses_dynamic_stack: false
    .vgpr_count:     256
    .vgpr_spill_count: 0
    .wavefront_size: 64
